# combined: DMA chunks spread between MFMA pairs in gemm<4,2> loops, batched residual epilogue, MLA softmax shift folded into MFMA accumulator init
# speedup vs baseline: 1.0529x; 1.0113x over previous
; DI int get_tid() { int t = threadIdx.x; asm volatile("" : "+v"(t)); return t; }
; template <int DQK, int DV, bool BIAS> ...
;     ...
;   const int tid = get_tid(), lane = tid & 63, l32 = lane & 31, hh = lane >> 5;
;   int koff[NKC], kch[NKC];
; #pragma unroll
;   for (int i = 0; i < NKC; ++i) { const int c = min(tid + NT * i, KCH - 1); kch[i] = c * 8; koff[i] = (c / CPR) * KROW + (c % CPR) * 16; }
;   const int vrow = tid >> 3, vcol = tid & 7;
;   float m = -INFINITY, lsum = 0.f;
; #pragma unroll
;   for (int vb = 0; vb < DV / 32; ++vb)
; #pragma unroll
;     for (int i = 0; i < 16; ++i) o[vb][i] = 0.f;
;   u32x4 rk[2][NKC], rv[2][NVC];
;   const int last = nt_wg - 1;
;     ...
;   __syncthreads();
;   RING_LOAD(0)
;   RING_STORE(0)
;   RING_LOAD(2)
;   __syncthreads();
; DI void mla_item(const Params& p, int b, int h, int qb, char* lds) {
;     ...
;   const int s = qb * 256 + wave * 32 + l32; const int t = b * 4096 + s;
;   const u16* qp = (const u16*)(ws + R_Q) + ((size_t)(b * 8 + h) * 4096 + s) * 96;
;   bf16x8 qf[6];
; #pragma unroll
;   for (int st = 0; st < 6; ++st) qf[st] = *(const bf16x8*)(qp + st * 16 + hh * 8);
;   f32x16 o[2];
;   attn_ring<96, 64, false>(qf, (const u16*)(ws + R_K) + (size_t)(b * 8 + h) * 4096 * 96, (const u16*)(ws + R_V) + (size_t)(b * 8 + h) * 64 * 4096,
;                            4096, 4 * qb + 4, 4 * qb + 1 + (wave >> 1), o, lds, nullptr, 0, 0, nullptr, nullptr);
.LBB0_73:
	s_and_b64 vcc, exec, s[0:1]
	s_cbranch_vccz .LBB0_84
	s_sub_i32 s0, s58, 64
	s_lshr_b32 s0, s0, 3
	s_sub_i32 s36, 15, s0
	s_mov_b64 s[0:1], s[30:31]
	v_mov_b32_e32 v32, v145
	s_and_b32 s33, s58, 7
	v_ashrrev_i32_e32 v0, 1, v32
	v_and_b32_e32 v0, 0xffffffe0, v0
	v_lshl_add_u32 v0, s36, 8, v0
	v_readlane_b32 s8, v254, 11
	v_and_or_b32 v116, v32, 31, v0
	s_or_b32 s37, s33, s8
	s_lshl_b32 s80, s37, 12
	v_ashrrev_i32_e32 v117, 31, v116
	v_lshl_add_u64 v[2:3], s[80:81], 0, v[116:117]
	s_waitcnt lgkmcnt(0)
	v_mov_b64_e32 v[4:5], s[0:1]
	s_movk_i32 s34, 0xc0
	v_lshrrev_b32_e32 v0, 2, v32
	v_mad_u64_u32 v[4:5], s[8:9], v2, s34, v[4:5]
	v_and_b32_e32 v114, 8, v0
	v_mad_i32_i24 v5, v3, s34, v5
	v_lshlrev_b32_e32 v0, 1, v114
	v_lshl_add_u64 v[2:3], v[4:5], 0, v[0:1]
	s_mov_b64 s[4:5], 0x119b1000
	s_mov_b32 s8, 0x119b1000
	v_lshl_add_u64 v[4:5], v[2:3], 0, s[4:5]
	v_add_co_u32_e32 v2, vcc, s8, v2
	s_mul_i32 s8, s37, 0xc0000
	s_add_u32 s38, s0, s8
	s_addc_u32 s39, s1, 0
	s_add_u32 s34, s38, 0x149b1000
	v_mov_b32_e32 v33, v145
	v_addc_co_u32_e32 v3, vcc, 0, v3, vcc
	flat_load_dwordx4 v[66:69], v[4:5] offset:32
	flat_load_dwordx4 v[70:73], v[4:5] offset:64
	flat_load_dwordx4 v[74:77], v[4:5] offset:96
	flat_load_dwordx4 v[78:81], v[4:5] offset:128
	flat_load_dwordx4 v[82:85], v[2:3]
	flat_load_dwordx4 v[86:89], v[4:5] offset:160
	s_addc_u32 s35, s39, 0
	s_lshl_b32 s8, s37, 19
	s_add_u32 s8, s0, s8
	v_ashrrev_i32_e32 v26, 3, v33
	v_min_i32_e32 v0, 0xff, v33
	v_ashrrev_i32_e32 v27, 31, v26
	s_addc_u32 s9, s1, 0
	v_add_u32_e32 v35, 0x200, v0
	v_lshlrev_b64 v[4:5], 13, v[26:27]
	v_lshlrev_b32_e32 v0, 4, v33
	v_lshl_add_u64 v[4:5], s[8:9], 0, v[4:5]
	v_and_b32_e32 v0, 0x70, v0
	v_min_i32_e32 v34, 0x2ff, v33
	v_lshl_add_u64 v[8:9], v[4:5], 0, v[0:1]
	s_mov_b64 s[8:9], 0x179b1000
	s_lshl_b32 s37, s36, 2
	v_lshlrev_b32_e32 v2, 3, v34
	v_lshlrev_b32_e32 v6, 3, v35
	v_lshl_add_u64 v[118:119], v[8:9], 0, s[8:9]
	s_mov_b32 s8, 0x179b1000
	v_ashrrev_i32_e32 v3, 31, v2
	v_ashrrev_i32_e32 v7, 31, v6
	v_add_co_u32_e32 v10, vcc, s8, v8
	s_add_u32 s8, s38, 0x149b4000
	v_lshlrev_b64 v[120:121], 1, v[2:3]
	v_lshlrev_b64 v[122:123], 1, v[6:7]
	s_addc_u32 s9, s39, 0
	v_lshl_add_u64 v[14:15], s[8:9], 0, v[120:121]
	v_lshl_add_u64 v[18:19], s[8:9], 0, v[122:123]
	s_add_u32 s8, s38, 0x149b7000
	s_addc_u32 s9, s39, 0
	v_lshl_add_u64 v[2:3], s[34:35], 0, v[120:121]
	v_lshl_add_u64 v[28:29], s[8:9], 0, v[120:121]
	v_lshl_add_u64 v[30:31], s[8:9], 0, v[122:123]
	s_add_u32 s8, s38, 0x149ba000
	s_waitcnt lgkmcnt(0)
	s_barrier
	global_load_dwordx4 v[2:5], v[2:3], off
	v_lshl_add_u64 v[6:7], s[34:35], 0, v[122:123]
	v_addc_co_u32_e32 v11, vcc, 0, v9, vcc
	s_addc_u32 s9, s39, 0
	global_load_dwordx4 v[6:9], v[6:7], off
	s_nop 0
	global_load_dwordx4 v[10:13], v[10:11], off
	s_nop 0
	global_load_dwordx4 v[14:17], v[14:15], off
	s_nop 0
	global_load_dwordx4 v[18:21], v[18:19], off
	s_nop 0
	global_load_dwordx4 v[22:25], v[118:119], off offset:128
	global_load_dwordx4 v[94:97], v[28:29], off
	global_load_dwordx4 v[90:93], v[30:31], off
	global_load_dwordx4 v[98:101], v[118:119], off offset:256
	v_lshl_add_u64 v[28:29], s[8:9], 0, v[120:121]
	v_lshl_add_u64 v[30:31], s[8:9], 0, v[122:123]
	global_load_dwordx4 v[102:105], v[28:29], off
	global_load_dwordx4 v[106:109], v[30:31], off
	global_load_dwordx4 v[110:113], v[118:119], off offset:384
	v_ashrrev_i32_e32 v27, 7, v32
	s_mov_b32 s8, 0x2aaaaaab
	v_add3_u32 v115, v27, s37, 1
	v_mul_hi_i32 v27, v34, s8
	v_lshrrev_b32_e32 v28, 31, v27
	v_lshrrev_b32_e32 v27, 1, v27
	v_add_u32_e32 v27, v27, v28
	v_add_lshl_u32 v117, v27, v34, 4
	v_mul_hi_i32 v27, v35, s8
	v_lshrrev_b32_e32 v28, 31, v27
	v_lshrrev_b32_e32 v27, 1, v27
	v_add_u32_e32 v27, v27, v28
	s_movk_i32 s8, 0x90
	v_add_lshl_u32 v124, v27, v35, 4
	v_mul_lo_u32 v125, v26, s8
	v_add_u32_e32 v26, 0, v117
	v_and_b32_e32 v27, 31, v33
	s_or_b32 s37, s37, 3
	s_mov_b32 s36, 0
	v_mul_u32_u24_e32 v126, 0xd0, v27
	v_mul_u32_u24_e32 v128, 0x90, v27
	s_lshr_b32 s38, s37, 1
	v_mov_b32_e32 v27, v1
	v_mov_b32_e32 v28, v1
	v_mov_b32_e32 v29, v1
	v_mov_b32_e32 v30, v1
	v_mov_b32_e32 v31, v1
	v_mov_b32_e32 v32, v1
	v_mov_b32_e32 v130, 0xff800000
	v_mov_b32_e32 v198, 0
	v_mov_b32_e32 v199, 0
	v_mov_b32_e32 v200, 0
	v_mov_b32_e32 v201, 0
	v_mov_b32_e32 v202, 0
	v_mov_b32_e32 v203, 0
	v_mov_b32_e32 v204, 0
	v_mov_b32_e32 v205, 0
	v_mov_b32_e32 v206, 0
	v_mov_b32_e32 v207, 0
	v_mov_b32_e32 v208, 0
	v_mov_b32_e32 v209, 0
	v_mov_b32_e32 v210, 0
	v_mov_b32_e32 v211, 0
	v_mov_b32_e32 v212, 0
	v_mov_b32_e32 v213, 0
	v_mov_b32_e32 v214, 0xff800000
	v_mov_b32_e32 v129, 0
	s_mov_b32 s39, 0
	s_waitcnt vmcnt(0)
	ds_write_b128 v26, v[2:5]
	v_add_u32_e32 v2, 0, v124
	v_add3_u32 v3, 0, v125, v0
	v_mov_b32_e32 v4, v1
	ds_write_b128 v2, v[6:9]
	ds_write_b128 v3, v[10:13] offset:13312
	ds_write_b128 v26, v[14:17] offset:22528
	ds_write_b128 v2, v[18:21] offset:22528
	ds_write_b128 v3, v[22:25] offset:35840
	v_lshrrev_b32_e32 v2, 1, v33
	v_and_b32_e32 v127, 16, v2
	v_mov_b32_e32 v18, v1
	v_mov_b32_e32 v19, v1
	v_mov_b32_e32 v20, v1
	v_mov_b32_e32 v21, v1
	v_mov_b32_e32 v22, v1
	v_mov_b32_e32 v23, v1
	v_mov_b32_e32 v24, v1
	v_mov_b32_e32 v25, v1
	v_mov_b32_e32 v26, v1
	v_mov_b32_e32 v33, v1
	v_mov_b32_e32 v2, v1
	v_mov_b32_e32 v3, v1
	v_mov_b32_e32 v5, v1
	v_mov_b32_e32 v6, v1
	v_mov_b32_e32 v7, v1
	v_mov_b32_e32 v8, v1
	v_mov_b32_e32 v9, v1
	v_mov_b32_e32 v10, v1
	v_mov_b32_e32 v11, v1
	v_mov_b32_e32 v12, v1
	v_mov_b32_e32 v13, v1
	v_mov_b32_e32 v14, v1
	v_mov_b32_e32 v15, v1
	v_mov_b32_e32 v16, v1
	v_mov_b32_e32 v17, v1
	s_waitcnt lgkmcnt(0)
	s_barrier

; DI unsigned pack2(float a, float b) { f2_t v = {a, b}; bf2_t r = __builtin_convertvector(v, bf2_t); return __builtin_bit_cast(unsigned, r); }
; DI f32x16 mfma(bf16x8 a, bf16x8 b, f32x16 c) { return __builtin_amdgcn_mfma_f32_32x32x16_bf16(a, b, c, 0, 0, 0); }
; template <int DQK, int DV, bool BIAS>
; DI void attn_tile(const char* cur, const bf16x8* qf, f32x16* o, float& m, float& lsum, int kt, int l32, int hh,
;                   const int* __restrict__ posb, int qpos, int qmin, const int* __restrict__ kpmax, const float* lut) {
;     ...
;       const float sh = m - cb;
;       float rs = 0.f;
; #pragma unroll
;       for (int i = 0; i < 16; ++i) { s0[i] = __builtin_amdgcn_exp2f(s0[i] - sh); rs += s0[i]; }
; #pragma unroll
;       for (int i = 0; i < 16; ++i) { s1[i] = __builtin_amdgcn_exp2f(s1[i] - sh); rs += s1[i]; }
;       lsum += rs;
;       bf16x8 pf[4];
; #pragma unroll
;       for (int ks = 0; ks < 4; ++ks) {
;         const f32x16& sv = (ks < 2) ? s0 : s1;
;         const int b0 = (ks & 1) * 8;
;         uint4 u;
;         u.x = pack2(sv[b0 + 0], sv[b0 + 1]); u.y = pack2(sv[b0 + 2], sv[b0 + 3]);
;         u.z = pack2(sv[b0 + 4], sv[b0 + 5]); u.w = pack2(sv[b0 + 6], sv[b0 + 7]);
;         pf[ks] = __builtin_bit_cast(bf16x8, u);
;       }
; #pragma unroll
;       for (int vb = 0; vb < DV / 32; ++vb)
; #pragma unroll
;         for (int ks = 0; ks < 4; ++ks) {
;           const bf16x8 a = *(const bf16x8*)(cur + KB + (vb * 32 + l32) * VROW + ks * 32 + hh * 16);
;           o[vb] = mfma(a, pf[ks], o[vb]);
;         }
.LBB0_76:
	v_exp_f32_e32 v50, v50
	v_exp_f32_e32 v51, v51
	v_exp_f32_e32 v52, v52
	v_exp_f32_e32 v53, v53
	v_add_f32_e32 v131, 0, v50
	v_exp_f32_e32 v54, v54
	v_add_f32_e32 v131, v51, v131
	v_exp_f32_e32 v55, v55
	v_add_f32_e32 v131, v52, v131
	v_exp_f32_e32 v56, v56
	v_add_f32_e32 v131, v53, v131
	v_exp_f32_e32 v57, v57
	v_add_f32_e32 v131, v54, v131
	v_exp_f32_e32 v58, v58
	v_add_f32_e32 v131, v55, v131
	v_exp_f32_e32 v59, v59
	v_add_f32_e32 v131, v56, v131
	v_exp_f32_e32 v60, v60
	v_add_f32_e32 v131, v57, v131
	v_exp_f32_e32 v61, v61
	v_add_f32_e32 v131, v58, v131
	v_exp_f32_e32 v62, v62
	v_add_f32_e32 v131, v59, v131
	v_exp_f32_e32 v63, v63
	v_add_f32_e32 v131, v60, v131
	v_exp_f32_e32 v64, v64
	v_add_f32_e32 v131, v61, v131
	v_exp_f32_e32 v65, v65
	v_add_f32_e32 v131, v62, v131
	v_exp_f32_e32 v34, v34
	v_add_f32_e32 v131, v63, v131
	v_exp_f32_e32 v35, v35
	v_add_f32_e32 v131, v64, v131
	v_exp_f32_e32 v36, v36
	v_add_f32_e32 v131, v65, v131
	v_exp_f32_e32 v37, v37
	v_add_f32_e32 v131, v34, v131
	v_exp_f32_e32 v132, v38
	v_add_f32_e32 v131, v35, v131
	v_add_f32_e32 v131, v36, v131
	v_add_f32_e32 v131, v37, v131
	v_add_f32_e32 v38, v132, v131
	v_exp_f32_e32 v131, v39
	v_exp_f32_e32 v133, v40
	v_mov_b32_e32 v39, v41
	v_exp_f32_e32 v41, v41
	v_exp_f32_e32 v134, v42
	v_exp_f32_e32 v135, v43
	v_exp_f32_e32 v136, v44
	v_exp_f32_e32 v137, v45
	v_exp_f32_e32 v138, v46
	v_exp_f32_e32 v139, v47
	v_cvt_pk_bf16_f32 v42, v58, v59
	v_exp_f32_e32 v140, v48
	v_mov_b32_e32 v39, v49
	v_cvt_pk_bf16_f32 v46, v50, v51
	v_cvt_pk_bf16_f32 v47, v52, v53
	v_cvt_pk_bf16_f32 v48, v54, v55
	v_cvt_pk_bf16_f32 v49, v56, v57
	s_waitcnt lgkmcnt(0)
	s_nop 1
	v_mfma_f32_32x32x16_bf16 v[18:33], v[148:151], v[46:49], v[18:33]
	v_mfma_f32_32x32x16_bf16 v[2:17], v[164:167], v[46:49], v[2:17]
	v_add_f32_e32 v38, v131, v38
	v_add_f32_e32 v38, v133, v38
	v_add_f32_e32 v38, v41, v38
	v_add_f32_e32 v38, v134, v38
	v_cvt_pk_bf16_f32 v43, v60, v61
	v_cvt_pk_bf16_f32 v44, v62, v63
	v_cvt_pk_bf16_f32 v45, v64, v65
	v_add_f32_e32 v38, v135, v38
	s_nop 0
	v_mfma_f32_32x32x16_bf16 v[18:33], v[152:155], v[42:45], v[18:33]
	v_mfma_f32_32x32x16_bf16 v[2:17], v[168:171], v[42:45], v[2:17]
	v_add_f32_e32 v38, v136, v38
	v_add_f32_e32 v38, v137, v38
	v_exp_f32_e32 v141, v39
	v_add_f32_e32 v38, v138, v38
	v_add_f32_e32 v38, v139, v38
	v_add_f32_e32 v38, v140, v38
	v_add_f32_e32 v38, v141, v38
	v_add_f32_e32 v129, v129, v38
	v_cvt_pk_bf16_f32 v38, v34, v35
	v_cvt_pk_bf16_f32 v39, v36, v37
	v_cvt_pk_bf16_f32 v40, v132, v131
	v_cvt_pk_bf16_f32 v41, v133, v41
	v_cvt_pk_bf16_f32 v34, v134, v135
	v_cvt_pk_bf16_f32 v35, v136, v137
	s_nop 0
	v_mfma_f32_32x32x16_bf16 v[18:33], v[156:159], v[38:41], v[18:33]
	v_mfma_f32_32x32x16_bf16 v[2:17], v[172:175], v[38:41], v[2:17]
	v_cvt_pk_bf16_f32 v36, v138, v139
	v_cvt_pk_bf16_f32 v37, v140, v141
	s_nop 1
	v_mfma_f32_32x32x16_bf16 v[18:33], v[160:163], v[34:37], v[18:33]
	v_mfma_f32_32x32x16_bf16 v[2:17], v[176:179], v[34:37], v[2:17]

; DI float xmax32(float v) { const auto r = __builtin_amdgcn_permlane32_swap(__float_as_uint(v), __float_as_uint(v), false, false); return fmaxf(__uint_as_float(r[0]), __uint_as_float(r[1])); }
; DI f32x16 mfma(bf16x8 a, bf16x8 b, f32x16 c) { return __builtin_amdgcn_mfma_f32_32x32x16_bf16(a, b, c, 0, 0, 0); }
; template <int DQK, int DV, bool BIAS>
; DI void attn_tile(const char* cur, const bf16x8* qf, f32x16* o, float& m, float& lsum, int kt, int l32, int hh,
;                   const int* __restrict__ posb, int qpos, int qmin, const int* __restrict__ kpmax, const float* lut) {
;     ...
;       for (int st = 0; st < DQK / 16; ++st) {
;         const bf16x8 a0 = *(const bf16x8*)(cur + l32 * KROW + st * 32 + hh * 16);
;         const bf16x8 a1 = *(const bf16x8*)(cur + (32 + l32) * KROW + st * 32 + hh * 16);
;         s0 = mfma(a0, qf[st], s0);
;         s1 = mfma(a1, qf[st], s1);
;       }
;       float cb = 0.f;
;       if (BIAS) {
;         const int kmx = kpmax[kt];
;         if (kmx - qmin <= -128) {
;           cb = lut[0];
;         } else {
; #pragma unroll
;           for (int j = 0; j < 4; ++j) {
;             const int4 k0 = *(const int4*)(posb + kt * 64 + 8 * j + 4 * hh);
;             const int4 k1 = *(const int4*)(posb + kt * 64 + 32 + 8 * j + 4 * hh);
;             const int ka[4] = {k0.x, k0.y, k0.z, k0.w}, kb[4] = {k1.x, k1.y, k1.z, k1.w};
; #pragma unroll
;             for (int r = 0; r < 4; ++r) {
;               s0[4 * j + r] += lut[min(max(ka[r] - qpos, -128), 128) + 128];
;               s1[4 * j + r] += lut[min(max(kb[r] - qpos, -128), 128) + 128];
;             }
;           }
;         }
;       }
;       float mx = s0[0];
; #pragma unroll
;       for (int i = 1; i < 16; ++i) mx = fmaxf(mx, s0[i]);
; #pragma unroll
;       for (int i = 0; i < 16; ++i) mx = fmaxf(mx, s1[i]);
;       mx = xmax32(mx) + cb;
;       if (__any(mx > m + 8.f)) {
;         const float mnew = fmaxf(m, mx);
;         const float alpha = __builtin_amdgcn_exp2f(m - mnew);
;         m = mnew;
;         lsum *= alpha;
; #pragma unroll
;         for (int vb = 0; vb < DV / 32; ++vb)
; #pragma unroll
;           for (int i = 0; i < 16; ++i) o[vb][i] *= alpha;
;       }
.LBB0_78:
	s_or_b32 s8, s59, s36
	v_cmp_lt_i32_e32 vcc, s8, v115
	s_and_saveexec_b64 s[52:53], vcc
	s_cbranch_execz .LBB0_77
	s_mul_i32 s8, s59, 0x5800
	s_add_i32 s8, s47, s8
	v_add3_u32 v131, s8, v126, v127
	v_add3_u32 v142, s8, v127, v128
	ds_read_b128 v[34:37], v131
	ds_read_b128 v[38:41], v131 offset:32
	ds_read_b128 v[42:45], v131 offset:64
	ds_read_b128 v[46:49], v131 offset:96
	ds_read_b128 v[132:135], v131 offset:128
	ds_read_b128 v[136:139], v131 offset:160
	ds_read_b128 v[234:237], v131 offset:6656
	ds_read_b128 v[238:241], v131 offset:6688
	ds_read_b128 v[242:245], v131 offset:6720
	s_waitcnt lgkmcnt(8)
	v_mfma_f32_32x32x16_bf16 v[50:65], v[34:37], v[82:85], v[198:213]
	ds_read_b128 v[246:249], v131 offset:6752
	ds_read_b128 v[250:253], v131 offset:6784
	ds_read_b128 v[190:193], v131 offset:6816
	s_waitcnt lgkmcnt(10)
	v_mfma_f32_32x32x16_bf16 v[50:65], v[38:41], v[66:69], v[50:65]
	s_waitcnt lgkmcnt(9)
	v_mfma_f32_32x32x16_bf16 v[50:65], v[42:45], v[70:73], v[50:65]
	s_waitcnt lgkmcnt(8)
	v_mfma_f32_32x32x16_bf16 v[50:65], v[46:49], v[74:77], v[50:65]
	s_waitcnt lgkmcnt(7)
	v_mfma_f32_32x32x16_bf16 v[50:65], v[132:135], v[78:81], v[50:65]
	s_waitcnt lgkmcnt(6)
	v_mfma_f32_32x32x16_bf16 v[50:65], v[136:139], v[86:89], v[50:65]
	ds_read_b128 v[148:151], v142 offset:13312
	ds_read_b128 v[152:155], v142 offset:13344
	ds_read_b128 v[156:159], v142 offset:13376
	ds_read_b128 v[160:163], v142 offset:13408
	ds_read_b128 v[164:167], v142 offset:17920
	ds_read_b128 v[168:171], v142 offset:17952
	ds_read_b128 v[172:175], v142 offset:17984
	ds_read_b128 v[176:179], v142 offset:18016
	s_waitcnt lgkmcnt(13)
	v_mfma_f32_32x32x16_bf16 v[34:49], v[234:237], v[82:85], v[198:213]
	s_waitcnt lgkmcnt(12)
	v_mfma_f32_32x32x16_bf16 v[34:49], v[238:241], v[66:69], v[34:49]
	s_waitcnt lgkmcnt(11)
	v_mfma_f32_32x32x16_bf16 v[34:49], v[242:245], v[70:73], v[34:49]
	s_waitcnt lgkmcnt(10)
	v_mfma_f32_32x32x16_bf16 v[34:49], v[246:249], v[74:77], v[34:49]
	v_max_f32_e32 v140, v50, v50
	v_max_f32_e32 v131, v51, v51
	v_max_f32_e32 v131, v140, v131
	v_max3_f32 v131, v131, v52, v53
	s_waitcnt lgkmcnt(9)
	v_mfma_f32_32x32x16_bf16 v[34:49], v[250:253], v[78:81], v[34:49]
	v_max3_f32 v131, v131, v54, v55
	v_max3_f32 v131, v131, v56, v57
	v_max3_f32 v131, v131, v58, v59
	v_max3_f32 v131, v131, v60, v61
	s_waitcnt lgkmcnt(8)
	v_mfma_f32_32x32x16_bf16 v[34:49], v[190:193], v[86:89], v[34:49]
	v_max3_f32 v131, v131, v62, v63
	v_max3_f32 v131, v131, v64, v65
	s_nop 9
	v_max3_f32 v131, v131, v34, v35
	v_max3_f32 v131, v131, v36, v37
	v_max3_f32 v131, v131, v38, v39
	v_max3_f32 v131, v131, v40, v41
	v_max3_f32 v131, v131, v42, v43
	v_max3_f32 v131, v131, v44, v45
	v_max3_f32 v131, v131, v46, v47
	v_max3_f32 v131, v131, v48, v49
	v_mov_b32_e32 v132, v131
	s_nop 1
	v_permlane32_swap_b32_e32 v131, v132
	v_max_f32_e32 v132, v132, v132
	v_max_f32_e32 v131, v131, v131
	v_max_f32_e32 v131, v131, v132
	v_cmp_gt_f32_e32 vcc, v131, v214
	s_cbranch_vccz .LBB0_76
	v_exp_f32_e64 v132, -v131
	v_mov_b32_e32 v214, 0x41000000
	v_mul_f32_e32 v129, v129, v132
	v_mul_f32_e32 v18, v18, v132
	v_mul_f32_e32 v19, v19, v132
	v_mul_f32_e32 v20, v20, v132
	v_mul_f32_e32 v21, v21, v132
	v_mul_f32_e32 v22, v22, v132
	v_mul_f32_e32 v23, v23, v132
	v_mul_f32_e32 v24, v24, v132
	v_mul_f32_e32 v25, v25, v132
	v_mul_f32_e32 v26, v26, v132
	v_mul_f32_e32 v27, v27, v132
	v_mul_f32_e32 v28, v28, v132
	v_mul_f32_e32 v29, v29, v132
	v_mul_f32_e32 v30, v30, v132
	v_mul_f32_e32 v31, v31, v132
	v_mul_f32_e32 v32, v32, v132
	v_mul_f32_e32 v33, v33, v132
	v_mul_f32_e32 v2, v2, v132
	v_mul_f32_e32 v3, v3, v132
	v_mul_f32_e32 v4, v4, v132
	v_mul_f32_e32 v5, v5, v132
	v_mul_f32_e32 v6, v6, v132
	v_mul_f32_e32 v7, v7, v132
	v_mul_f32_e32 v8, v8, v132
	v_mul_f32_e32 v9, v9, v132
	v_mul_f32_e32 v10, v10, v132
	v_mul_f32_e32 v11, v11, v132
	v_mul_f32_e32 v12, v12, v132
	v_mul_f32_e32 v13, v13, v132
	v_mul_f32_e32 v14, v14, v132
	v_mul_f32_e32 v15, v15, v132
	v_mul_f32_e32 v16, v16, v132
	v_mul_f32_e32 v17, v17, v132
	v_sub_f32_e32 v198, v198, v131
	v_sub_f32_e32 v199, v199, v131
	v_sub_f32_e32 v200, v200, v131
	v_sub_f32_e32 v201, v201, v131
	v_sub_f32_e32 v202, v202, v131
	v_sub_f32_e32 v203, v203, v131
	v_sub_f32_e32 v204, v204, v131
	v_sub_f32_e32 v205, v205, v131
	v_sub_f32_e32 v206, v206, v131
	v_sub_f32_e32 v207, v207, v131
	v_sub_f32_e32 v208, v208, v131
	v_sub_f32_e32 v209, v209, v131
	v_sub_f32_e32 v210, v210, v131
	v_sub_f32_e32 v211, v211, v131
	v_sub_f32_e32 v212, v212, v131
	v_sub_f32_e32 v213, v213, v131
	v_sub_f32_e32 v50, v50, v131
	v_sub_f32_e32 v51, v51, v131
	v_sub_f32_e32 v52, v52, v131
	v_sub_f32_e32 v53, v53, v131
	v_sub_f32_e32 v54, v54, v131
	v_sub_f32_e32 v55, v55, v131
	v_sub_f32_e32 v56, v56, v131
	v_sub_f32_e32 v57, v57, v131
	v_sub_f32_e32 v58, v58, v131
	v_sub_f32_e32 v59, v59, v131
	v_sub_f32_e32 v60, v60, v131
	v_sub_f32_e32 v61, v61, v131
	v_sub_f32_e32 v62, v62, v131
	v_sub_f32_e32 v63, v63, v131
	v_sub_f32_e32 v64, v64, v131
	v_sub_f32_e32 v65, v65, v131
	v_sub_f32_e32 v34, v34, v131
	v_sub_f32_e32 v35, v35, v131
	v_sub_f32_e32 v36, v36, v131
	v_sub_f32_e32 v37, v37, v131
	v_sub_f32_e32 v38, v38, v131
	v_sub_f32_e32 v39, v39, v131
	v_sub_f32_e32 v40, v40, v131
	v_sub_f32_e32 v41, v41, v131
	v_sub_f32_e32 v42, v42, v131
	v_sub_f32_e32 v43, v43, v131
	v_sub_f32_e32 v44, v44, v131
	v_sub_f32_e32 v45, v45, v131
	v_sub_f32_e32 v46, v46, v131
	v_sub_f32_e32 v47, v47, v131
	v_sub_f32_e32 v48, v48, v131
	v_sub_f32_e32 v49, v49, v131
	s_branch .LBB0_76

; DI f32x16 mfma(bf16x8 a, bf16x8 b, f32x16 c) { return __builtin_amdgcn_mfma_f32_32x32x16_bf16(a, b, c, 0, 0, 0); }
;     ...
;   __syncthreads();
;   DMA_ISSUE(0, 0)
;   asm volatile("s_waitcnt vmcnt(0)" ::: "memory");
;   __builtin_amdgcn_s_barrier();
;   for (int kt = 0; kt < nk; ++kt) {
;     const char* cur = lds + (kt & 1) * DBUF;
;     if (kt + 1 < nk) DMA_ISSUE((kt + 1) & 1, kt + 1)
; #pragma unroll(NTB == 1 ? 2 : 4)
;     for (int s = 0; s < 4; ++s) {
;       const int ro = ((2 * s + hh) ^ xr) * 16;
;       bf16x8 bfr[NTB];
; #pragma unroll
;       for (int tb = 0; tb < NTB; ++tb) bfr[tb] = *(const bf16x8*)(cur + bbase + tb * 32 * DROW + ro);
; #pragma unroll
;       for (int fb = 0; fb < NFB; ++fb) {
;         const bf16x8 afr = *(const bf16x8*)(cur + abase + fb * 32 * DROW + ro);
; #pragma unroll
;         for (int tb = 0; tb < NTB; ++tb) acc[tb * NFB + fb] = mfma(afr, bfr[tb], acc[tb * NFB + fb]);
;       }
;     }
;     asm volatile("s_waitcnt vmcnt(0) lgkmcnt(0)" ::: "memory");
;     __builtin_amdgcn_s_barrier();
;   }
.LBB0_149:
	s_add_i32 s8, s7, 0xffff0000
	s_and_b32 s8, s8, 0x10000
	v_add_u32_e32 v184, s8, v152
	v_add_u32_e32 v186, s8, v154
	v_add_u32_e32 v189, v184, v153
	v_add_u32_e32 v194, v186, v153
	ds_read_b128 v[234:237], v189 offset:32768
	ds_read_b128 v[238:241], v189 offset:36864
	ds_read_b128 v[250:253], v194
	ds_read_b128 v[180:183], v194 offset:4096
	ds_read_b128 v[190:193], v194 offset:8192
	ds_read_b128 v[164:167], v194 offset:12288
	v_add_u32_e32 v189, v184, v150
	v_add_u32_e32 v194, v186, v150
	ds_read_b128 v[242:245], v189 offset:32768
	ds_read_b128 v[246:249], v189 offset:36864
	s_waitcnt lgkmcnt(5)
	v_mfma_f32_32x32x16_bf16 v[114:129], v[250:253], v[234:237], v[114:129]
	v_mfma_f32_32x32x16_bf16 v[50:65], v[250:253], v[238:241], v[50:65]
	ds_read_b128 v[250:253], v194
	s_and_b32 s9, s7, 0x10000
	v_add_u32_e32 v155, s9, v151
	v_lshl_add_u64 v[156:157], v[138:139], 0, s[10:11]
	s_mov_b64 s[34:35], 0x1390080
	v_readfirstlane_b32 s9, v155
	v_add_u32_e32 v160, 0x2000, v155
	v_lshl_add_u64 v[158:159], v[156:157], 0, s[34:35]
	s_mov_b32 m0, s9
	s_mov_b64 s[34:35], 0x13b0080
	v_readfirstlane_b32 s9, v160
	v_add_u32_e32 v160, 0x4000, v155
	global_load_lds_dwordx4 v[158:159], off
	s_waitcnt lgkmcnt(5)
	v_mfma_f32_32x32x16_bf16 v[98:113], v[180:183], v[234:237], v[98:113]
	v_mfma_f32_32x32x16_bf16 v[34:49], v[180:183], v[238:241], v[34:49]
	ds_read_b128 v[180:183], v194 offset:4096
	v_lshl_add_u64 v[158:159], v[156:157], 0, s[34:35]
	s_mov_b32 m0, s9
	s_mov_b64 s[34:35], 0x13d0080
	v_readfirstlane_b32 s9, v160
	global_load_lds_dwordx4 v[158:159], off
	s_waitcnt lgkmcnt(5)
	v_mfma_f32_32x32x16_bf16 v[82:97], v[190:193], v[234:237], v[82:97]
	v_mfma_f32_32x32x16_bf16 v[18:33], v[190:193], v[238:241], v[18:33]
	ds_read_b128 v[190:193], v194 offset:8192
	v_lshl_add_u64 v[158:159], v[156:157], 0, s[34:35]
	s_mov_b32 m0, s9
	s_mov_b64 s[34:35], 0x13f0080
	global_load_lds_dwordx4 v[158:159], off
	s_waitcnt lgkmcnt(5)
	v_mfma_f32_32x32x16_bf16 v[66:81], v[164:167], v[234:237], v[66:81]
	v_mfma_f32_32x32x16_bf16 v[2:17], v[164:167], v[238:241], v[2:17]
	ds_read_b128 v[164:167], v194 offset:12288
	v_add_u32_e32 v158, 0x6000, v155
	v_lshl_add_u64 v[156:157], v[156:157], 0, s[34:35]
	v_readfirstlane_b32 s9, v158
	s_mov_b32 m0, s9
	v_add_u32_e32 v160, 0x8000, v155
	global_load_lds_dwordx4 v[156:157], off
	v_add_u32_e32 v189, v184, v149
	v_add_u32_e32 v194, v186, v149
	ds_read_b128 v[234:237], v189 offset:32768
	ds_read_b128 v[238:241], v189 offset:36864
	s_waitcnt lgkmcnt(5)
	v_mfma_f32_32x32x16_bf16 v[114:129], v[250:253], v[242:245], v[114:129]
	v_mfma_f32_32x32x16_bf16 v[50:65], v[250:253], v[246:249], v[50:65]
	ds_read_b128 v[250:253], v194
	v_lshl_add_u64 v[156:157], v[140:141], 0, s[10:11]
	v_readfirstlane_b32 s9, v160
	v_add_u32_e32 v160, 0xa000, v155
	s_add_i32 s8, s7, 0xffff0000
	v_lshl_add_u64 v[158:159], v[156:157], 0, s[68:69]
	s_mov_b32 m0, s9
	v_readfirstlane_b32 s9, v160
	v_add_u32_e32 v160, 0xc000, v155
	s_and_b32 s8, s8, 0x10000
	global_load_lds_dwordx4 v[158:159], off
	s_waitcnt lgkmcnt(5)
	v_mfma_f32_32x32x16_bf16 v[98:113], v[180:183], v[242:245], v[98:113]
	v_mfma_f32_32x32x16_bf16 v[34:49], v[180:183], v[246:249], v[34:49]
	ds_read_b128 v[180:183], v194 offset:4096
	v_lshl_add_u64 v[158:159], v[156:157], 0, s[2:3]
	s_mov_b32 m0, s9
	v_readfirstlane_b32 s9, v160
	v_add_u32_e32 v155, 0xe000, v155
	s_add_i32 s8, s8, 0
	global_load_lds_dwordx4 v[158:159], off
	s_waitcnt lgkmcnt(5)
	v_mfma_f32_32x32x16_bf16 v[82:97], v[190:193], v[242:245], v[82:97]
	v_mfma_f32_32x32x16_bf16 v[18:33], v[190:193], v[246:249], v[18:33]
	ds_read_b128 v[190:193], v194 offset:8192
	v_lshl_add_u64 v[158:159], v[156:157], 0, s[14:15]
	s_mov_b32 m0, s9
	v_readfirstlane_b32 s9, v155
	global_load_lds_dwordx4 v[158:159], off
	s_waitcnt lgkmcnt(5)
	v_mfma_f32_32x32x16_bf16 v[66:81], v[164:167], v[242:245], v[66:81]
	v_mfma_f32_32x32x16_bf16 v[2:17], v[164:167], v[246:249], v[2:17]
	ds_read_b128 v[164:167], v194 offset:12288
	v_lshl_add_u64 v[156:157], v[156:157], 0, s[40:41]
	s_mov_b32 m0, s9
	v_add_u32_e32 v155, s8, v152
	v_add_u32_e32 v168, s8, v154
	global_load_lds_dwordx4 v[156:157], off
	v_add_u32_e32 v189, v184, v0
	v_add_u32_e32 v194, v186, v0
	ds_read_b128 v[242:245], v189 offset:32768
	ds_read_b128 v[246:249], v189 offset:36864
	s_waitcnt lgkmcnt(5)
	v_mfma_f32_32x32x16_bf16 v[114:129], v[250:253], v[234:237], v[114:129]
	v_mfma_f32_32x32x16_bf16 v[50:65], v[250:253], v[238:241], v[50:65]
	ds_read_b128 v[250:253], v194
	s_add_u32 s10, s10, 0x80
	s_addc_u32 s11, s11, 0
	s_add_i32 s7, s7, 0x10000
	s_cmpk_eq_i32 s10, 0x780
	s_waitcnt lgkmcnt(5)
	v_mfma_f32_32x32x16_bf16 v[98:113], v[180:183], v[234:237], v[98:113]
	v_mfma_f32_32x32x16_bf16 v[34:49], v[180:183], v[238:241], v[34:49]
	ds_read_b128 v[180:183], v194 offset:4096
	s_waitcnt lgkmcnt(5)
	v_mfma_f32_32x32x16_bf16 v[82:97], v[190:193], v[234:237], v[82:97]
	v_mfma_f32_32x32x16_bf16 v[18:33], v[190:193], v[238:241], v[18:33]
	ds_read_b128 v[190:193], v194 offset:8192
	s_waitcnt lgkmcnt(5)
	v_mfma_f32_32x32x16_bf16 v[66:81], v[164:167], v[234:237], v[66:81]
	v_mfma_f32_32x32x16_bf16 v[2:17], v[164:167], v[238:241], v[2:17]
	ds_read_b128 v[164:167], v194 offset:12288
	s_waitcnt lgkmcnt(3)
	v_mfma_f32_32x32x16_bf16 v[114:129], v[250:253], v[242:245], v[114:129]
	v_mfma_f32_32x32x16_bf16 v[50:65], v[250:253], v[246:249], v[50:65]
	s_waitcnt lgkmcnt(2)
	v_mfma_f32_32x32x16_bf16 v[98:113], v[180:183], v[242:245], v[98:113]
	v_mfma_f32_32x32x16_bf16 v[34:49], v[180:183], v[246:249], v[34:49]
	s_waitcnt lgkmcnt(1)
	v_mfma_f32_32x32x16_bf16 v[82:97], v[190:193], v[242:245], v[82:97]
	v_mfma_f32_32x32x16_bf16 v[18:33], v[190:193], v[246:249], v[18:33]
	s_waitcnt vmcnt(0) lgkmcnt(0)
	s_barrier
; DI f32x16 mfma(bf16x8 a, bf16x8 b, f32x16 c) { return __builtin_amdgcn_mfma_f32_32x32x16_bf16(a, b, c, 0, 0, 0); }
;     ...
;   for (int kt = 0; kt < nk; ++kt) {
;     const char* cur = lds + (kt & 1) * DBUF;
;     if (kt + 1 < nk) DMA_ISSUE((kt + 1) & 1, kt + 1)
; #pragma unroll(NTB == 1 ? 2 : 4)
;     for (int s = 0; s < 4; ++s) {
;       const int ro = ((2 * s + hh) ^ xr) * 16;
;       bf16x8 bfr[NTB];
; #pragma unroll
;       for (int tb = 0; tb < NTB; ++tb) bfr[tb] = *(const bf16x8*)(cur + bbase + tb * 32 * DROW + ro);
; #pragma unroll
;       for (int fb = 0; fb < NFB; ++fb) {
;         const bf16x8 afr = *(const bf16x8*)(cur + abase + fb * 32 * DROW + ro);
; #pragma unroll
;         for (int tb = 0; tb < NTB; ++tb) acc[tb * NFB + fb] = mfma(afr, bfr[tb], acc[tb * NFB + fb]);
;       }
;     }
;     asm volatile("s_waitcnt vmcnt(0) lgkmcnt(0)" ::: "memory");
;     __builtin_amdgcn_s_barrier();
;   }
; __global__ void __launch_bounds__(512) mega(Params p) {
;     ...
; #pragma unroll
;         for (int tb = 0; tb < 2; ++tb)
; #pragma unroll
;           for (int fb = 0; fb < 4; ++fb)
; #pragma unroll
;             for (int jq = 0; jq < 4; ++jq) {
;               const f32x16& a = acc[tb * 4 + fb];
;               const float a0 = fmaxf(a[4 * jq], 0.f) * r2[tb], a1 = fmaxf(a[4 * jq + 1], 0.f) * r2[tb], a2 = fmaxf(a[4 * jq + 2], 0.f) * r2[tb], a3 = fmaxf(a[4 * jq + 3], 0.f) * r2[tb];
	v_mfma_f32_32x32x16_bf16 v[66:81], v[164:167], v[242:245], v[66:81]
	v_mfma_f32_32x32x16_bf16 v[2:17], v[164:167], v[246:249], v[2:17]
	s_cbranch_scc0 .LBB0_149
	s_add_i32 s7, 0, 0x10000
	v_add_u32_e32 v162, s7, v152
	v_add_u32_e32 v163, s7, v154
	v_add_u32_e32 v151, v162, v153
	ds_read_b128 v[138:141], v151 offset:32768
	ds_read_b128 v[154:157], v151 offset:36864
	v_add_u32_e32 v151, v163, v153
	ds_read_b128 v[158:161], v151
	s_mov_b32 s8, 0x800000
	s_waitcnt lgkmcnt(0)
	v_mfma_f32_32x32x16_bf16 v[114:129], v[158:161], v[138:141], v[114:129]
	v_mfma_f32_32x32x16_bf16 v[50:65], v[158:161], v[154:157], v[50:65]
	ds_read_b128 v[158:161], v151 offset:4096
	s_waitcnt lgkmcnt(0)
	v_mfma_f32_32x32x16_bf16 v[98:113], v[158:161], v[138:141], v[98:113]
	v_mfma_f32_32x32x16_bf16 v[34:49], v[158:161], v[154:157], v[34:49]
	ds_read_b128 v[158:161], v151 offset:8192
	s_waitcnt lgkmcnt(0)
	v_mfma_f32_32x32x16_bf16 v[82:97], v[158:161], v[138:141], v[82:97]
	v_mfma_f32_32x32x16_bf16 v[18:33], v[158:161], v[154:157], v[18:33]
	ds_read_b128 v[158:161], v151 offset:12288
	v_add_u32_e32 v151, v162, v150
	v_add_u32_e32 v150, v163, v150
	s_waitcnt lgkmcnt(0)
	v_mfma_f32_32x32x16_bf16 v[66:81], v[158:161], v[138:141], v[66:81]
	v_mfma_f32_32x32x16_bf16 v[2:17], v[158:161], v[154:157], v[2:17]
	ds_read_b128 v[138:141], v151 offset:32768
	ds_read_b128 v[152:155], v151 offset:36864
	ds_read_b128 v[156:159], v150
	s_waitcnt lgkmcnt(0)
	v_mfma_f32_32x32x16_bf16 v[114:129], v[156:159], v[138:141], v[114:129]
	v_mfma_f32_32x32x16_bf16 v[50:65], v[156:159], v[152:155], v[50:65]
	ds_read_b128 v[156:159], v150 offset:4096
	s_waitcnt lgkmcnt(0)
	v_mfma_f32_32x32x16_bf16 v[98:113], v[156:159], v[138:141], v[98:113]
	v_mfma_f32_32x32x16_bf16 v[34:49], v[156:159], v[152:155], v[34:49]
	ds_read_b128 v[156:159], v150 offset:8192
	s_waitcnt lgkmcnt(0)
	v_mfma_f32_32x32x16_bf16 v[82:97], v[156:159], v[138:141], v[82:97]
	v_mfma_f32_32x32x16_bf16 v[18:33], v[156:159], v[152:155], v[18:33]
	ds_read_b128 v[156:159], v150 offset:12288
	v_add_u32_e32 v150, v162, v149
	v_add_u32_e32 v149, v163, v149
	s_waitcnt lgkmcnt(0)
	v_mfma_f32_32x32x16_bf16 v[66:81], v[156:159], v[138:141], v[66:81]
	v_mfma_f32_32x32x16_bf16 v[2:17], v[156:159], v[152:155], v[2:17]
	ds_read_b128 v[138:141], v150 offset:32768
	ds_read_b128 v[150:153], v150 offset:36864
	ds_read_b128 v[154:157], v149
	s_waitcnt lgkmcnt(0)
	v_mfma_f32_32x32x16_bf16 v[114:129], v[154:157], v[138:141], v[114:129]
	v_mfma_f32_32x32x16_bf16 v[50:65], v[154:157], v[150:153], v[50:65]
	ds_read_b128 v[154:157], v149 offset:4096
	s_waitcnt lgkmcnt(0)
	v_mfma_f32_32x32x16_bf16 v[98:113], v[154:157], v[138:141], v[98:113]
	v_mfma_f32_32x32x16_bf16 v[34:49], v[154:157], v[150:153], v[34:49]
	ds_read_b128 v[154:157], v149 offset:8192
	s_waitcnt lgkmcnt(0)
	v_mfma_f32_32x32x16_bf16 v[82:97], v[154:157], v[138:141], v[82:97]
	v_mfma_f32_32x32x16_bf16 v[18:33], v[154:157], v[150:153], v[18:33]
	ds_read_b128 v[154:157], v149 offset:12288
	v_add_u32_e32 v149, v162, v0
	v_add_u32_e32 v0, v163, v0
	s_waitcnt lgkmcnt(0)
	v_mfma_f32_32x32x16_bf16 v[66:81], v[154:157], v[138:141], v[66:81]
	v_mfma_f32_32x32x16_bf16 v[2:17], v[154:157], v[150:153], v[2:17]
	ds_read_b128 v[138:141], v149 offset:32768
	ds_read_b128 v[150:153], v149 offset:36864
	ds_read_b128 v[154:157], v0
	s_waitcnt lgkmcnt(0)
	v_mfma_f32_32x32x16_bf16 v[114:129], v[154:157], v[138:141], v[114:129]
	v_mfma_f32_32x32x16_bf16 v[50:65], v[154:157], v[150:153], v[50:65]
	ds_read_b128 v[154:157], v0 offset:4096
	s_nop 9
	v_max_f32_e32 v114, v114, v114
	v_max_f32_e32 v115, v115, v115
	v_max_f32_e32 v116, v116, v116
	v_max_f32_e32 v117, v117, v117
	v_max_f32_e32 v114, 0, v114
	v_max_f32_e32 v115, 0, v115
	s_waitcnt lgkmcnt(0)
	v_mfma_f32_32x32x16_bf16 v[98:113], v[154:157], v[138:141], v[98:113]
	v_max_f32_e32 v50, v50, v50
	v_max_f32_e32 v51, v51, v51
	v_max_f32_e32 v52, v52, v52
	v_max_f32_e32 v53, v53, v53
	v_max_f32_e32 v116, 0, v116
	v_max_f32_e32 v117, 0, v117
	v_max_f32_e32 v50, 0, v50
	v_mfma_f32_32x32x16_bf16 v[34:49], v[154:157], v[150:153], v[34:49]
	ds_read_b128 v[154:157], v0 offset:8192
	s_nop 2
	v_max_f32_e32 v98, v98, v98
	v_max_f32_e32 v99, v99, v99
	v_max_f32_e32 v100, v100, v100
	v_max_f32_e32 v101, v101, v101
	v_max_f32_e32 v98, 0, v98
	v_max_f32_e32 v99, 0, v99
	s_waitcnt lgkmcnt(0)
	v_mfma_f32_32x32x16_bf16 v[82:97], v[154:157], v[138:141], v[82:97]
	v_max_f32_e32 v34, v34, v34
	v_max_f32_e32 v35, v35, v35
	v_max_f32_e32 v36, v36, v36
	v_max_f32_e32 v37, v37, v37
	v_max_f32_e32 v100, 0, v100
	v_max_f32_e32 v101, 0, v101
	v_max_f32_e32 v51, 0, v51
	v_mfma_f32_32x32x16_bf16 v[18:33], v[154:157], v[150:153], v[18:33]
	ds_read_b128 v[154:157], v0 offset:12288
	s_waitcnt vmcnt(0) lgkmcnt(0)
	s_barrier
	s_waitcnt vmcnt(0) lgkmcnt(0)
	s_barrier
; DI float rstd4(const float* ssp, int t) {
;   return rsqrtf((ssp[t] + ssp[T_TOK + t] + ssp[2 * T_TOK + t] + ssp[3 * T_TOK + t]) * (1.f / 1024.f) + EPS);
; }
; __global__ void __launch_bounds__(512) mega(Params p) {
;     ...
;         __syncthreads();
;         float r2[2];
; #pragma unroll
;         for (int tb = 0; tb < 2; ++tb) r2[tb] = rstd4((const float*)(ws + OFF_SSX2), tt * 256 + wt * 64 + tb * 32 + l32);
; #pragma unroll
;         for (int tb = 0; tb < 2; ++tb)
; #pragma unroll
;           for (int fb = 0; fb < 4; ++fb)
; #pragma unroll
;             for (int jq = 0; jq < 4; ++jq) {
;               const f32x16& a = acc[tb * 4 + fb];
;               const float a0 = fmaxf(a[4 * jq], 0.f) * r2[tb], a1 = fmaxf(a[4 * jq + 1], 0.f) * r2[tb], a2 = fmaxf(a[4 * jq + 2], 0.f) * r2[tb], a3 = fmaxf(a[4 * jq + 3], 0.f) * r2[tb];
;               epi_put4(lds, wt * 64 + tb * 32 + l32, wf * 128 + fb * 32 + 8 * jq + 4 * hh, a0 * a0, a1 * a1, a2 * a2, a3 * a3);
;             }
	v_max_f32_e32 v82, v82, v82
	v_mfma_f32_32x32x16_bf16 v[66:81], v[154:157], v[138:141], v[66:81]
	v_lshl_or_b32 v138, s6, 8, v137
	v_ashrrev_i32_e32 v139, 31, v138
	v_lshl_add_u64 v[138:139], v[138:139], 2, s[52:53]
	s_mov_b32 s6, 0x20000
	flat_load_dword v141, v[138:139]
	v_max_f32_e32 v83, v83, v83
	v_max_f32_e32 v84, v84, v84
	v_mfma_f32_32x32x16_bf16 v[2:17], v[154:157], v[150:153], v[2:17]
	v_add_co_u32_e64 v150, s[6:7], s6, v138
	v_max_f32_e32 v85, v85, v85
	s_nop 0
	v_addc_co_u32_e64 v151, s[6:7], 0, v139, s[6:7]
	s_mov_b32 s6, 0x40000
	s_nop 0
	v_add_co_u32_e64 v154, s[6:7], s6, v138
	flat_load_dword v153, v[150:151]
	s_nop 0
	v_addc_co_u32_e64 v155, s[6:7], 0, v139, s[6:7]
	s_mov_b32 s6, 0x60000
	s_nop 0
	v_add_co_u32_e64 v158, s[6:7], s6, v138
	flat_load_dword v157, v[154:155]
	s_nop 0
	v_addc_co_u32_e64 v159, s[6:7], 0, v139, s[6:7]
	flat_load_dword v161, v[158:159]
	flat_load_dword v140, v[138:139] offset:128
	flat_load_dword v152, v[150:151] offset:128
	flat_load_dword v156, v[154:155] offset:128
	flat_load_dword v160, v[158:159] offset:128
	s_mov_b32 s6, 0x3a800000
	v_max_f32_e32 v66, v66, v66
	v_max_f32_e32 v67, v67, v67
	v_max_f32_e32 v68, v68, v68
	v_max_f32_e32 v69, v69, v69
	v_max_f32_e32 v18, v18, v18
	v_max_f32_e32 v19, v19, v19
	v_max_f32_e32 v20, v20, v20
	v_max_f32_e32 v21, v21, v21
	v_max_f32_e32 v2, v2, v2
	v_max_f32_e32 v3, v3, v3
	v_max_f32_e32 v4, v4, v4
	v_max_f32_e32 v5, v5, v5
	v_max_f32_e32 v82, 0, v82
	v_max_f32_e32 v83, 0, v83
	v_max_f32_e32 v84, 0, v84
	v_max_f32_e32 v85, 0, v85
	v_max_f32_e32 v66, 0, v66
	v_max_f32_e32 v67, 0, v67
	v_max_f32_e32 v68, 0, v68
	v_max_f32_e32 v69, 0, v69
	v_max_f32_e32 v52, 0, v52
	v_max_f32_e32 v53, 0, v53
	v_max_f32_e32 v34, 0, v34
	v_max_f32_e32 v35, 0, v35
	v_max_f32_e32 v36, 0, v36
	v_max_f32_e32 v37, 0, v37
	v_max_f32_e32 v18, 0, v18
	v_max_f32_e32 v19, 0, v19
	v_max_f32_e32 v20, 0, v20
	v_max_f32_e32 v21, 0, v21
	v_max_f32_e32 v2, 0, v2
	v_max_f32_e32 v3, 0, v3
	v_max_f32_e32 v4, 0, v4
	v_max_f32_e32 v5, 0, v5
	s_waitcnt vmcnt(0) lgkmcnt(0)
	v_pk_add_f32 v[138:139], v[140:141], v[152:153]
	s_nop 0
	v_pk_add_f32 v[138:139], v[138:139], v[156:157]
	s_nop 0
	v_pk_add_f32 v[138:139], v[138:139], v[160:161]
	s_nop 0
	v_pk_fma_f32 v[140:141], v[138:139], s[6:7], v[144:145] op_sel_hi:[1,0,0]
	s_nop 0
	v_mul_f32_e32 v0, 0x4b800000, v141
	v_cmp_gt_f32_e64 s[10:11], s8, v141
	v_cmp_gt_f32_e64 s[6:7], s8, v140
	s_nop 0
	v_cndmask_b32_e64 v0, v141, v0, s[10:11]
	v_rsq_f32_e32 v0, v0
	s_nop 0
	v_mul_f32_e32 v138, 0x45800000, v0
	v_cndmask_b32_e64 v138, v0, v138, s[10:11]
	v_mul_f32_e32 v0, 0x4b800000, v140
	v_cndmask_b32_e64 v0, v140, v0, s[6:7]
	v_rsq_f32_e32 v0, v0
	s_nop 0
	v_mul_f32_e32 v139, 0x45800000, v0
	v_cndmask_b32_e64 v0, v0, v139, s[6:7]
	v_pk_mul_f32 v[114:115], v[138:139], v[114:115] op_sel_hi:[0,1]
	v_pk_mul_f32 v[116:117], v[138:139], v[116:117] op_sel_hi:[0,1]
	v_pk_mul_f32 v[98:99], v[138:139], v[98:99] op_sel_hi:[0,1]
	v_pk_mul_f32 v[100:101], v[138:139], v[100:101] op_sel_hi:[0,1]
	v_pk_mul_f32 v[82:83], v[138:139], v[82:83] op_sel_hi:[0,1]
	v_pk_mul_f32 v[84:85], v[138:139], v[84:85] op_sel_hi:[0,1]
	v_pk_mul_f32 v[66:67], v[138:139], v[66:67] op_sel_hi:[0,1]
	v_pk_mul_f32 v[68:69], v[138:139], v[68:69] op_sel_hi:[0,1]
	v_pk_mul_f32 v[50:51], v[0:1], v[50:51] op_sel_hi:[0,1]
	v_pk_mul_f32 v[52:53], v[0:1], v[52:53] op_sel_hi:[0,1]
	v_pk_mul_f32 v[34:35], v[0:1], v[34:35] op_sel_hi:[0,1]
	v_pk_mul_f32 v[36:37], v[0:1], v[36:37] op_sel_hi:[0,1]
	v_pk_mul_f32 v[18:19], v[0:1], v[18:19] op_sel_hi:[0,1]
	v_pk_mul_f32 v[20:21], v[0:1], v[20:21] op_sel_hi:[0,1]
	v_pk_mul_f32 v[2:3], v[0:1], v[2:3] op_sel_hi:[0,1]
	v_pk_mul_f32 v[4:5], v[0:1], v[4:5] op_sel_hi:[0,1]
	v_pk_mul_f32 v[114:115], v[114:115], v[114:115]
	v_pk_mul_f32 v[116:117], v[116:117], v[116:117]
	v_pk_mul_f32 v[98:99], v[98:99], v[98:99]
	v_pk_mul_f32 v[100:101], v[100:101], v[100:101]
	v_pk_mul_f32 v[82:83], v[82:83], v[82:83]
	v_pk_mul_f32 v[84:85], v[84:85], v[84:85]
	v_pk_mul_f32 v[66:67], v[66:67], v[66:67]
	v_pk_mul_f32 v[68:69], v[68:69], v[68:69]
	v_pk_mul_f32 v[50:51], v[50:51], v[50:51]
	v_pk_mul_f32 v[52:53], v[52:53], v[52:53]
	v_pk_mul_f32 v[34:35], v[34:35], v[34:35]
	v_pk_mul_f32 v[36:37], v[36:37], v[36:37]
	v_pk_mul_f32 v[18:19], v[18:19], v[18:19]
	v_pk_mul_f32 v[20:21], v[20:21], v[20:21]
	v_pk_mul_f32 v[2:3], v[2:3], v[2:3]
	v_pk_mul_f32 v[4:5], v[4:5], v[4:5]
	v_cvt_pk_bf16_f32 v114, v114, v115
	v_cvt_pk_bf16_f32 v115, v116, v117
	v_max_f32_e32 v116, v118, v118
	v_max_f32_e32 v117, v119, v119
	v_max_f32_e32 v118, v120, v120
	v_max_f32_e32 v119, v121, v121
	v_cvt_pk_bf16_f32 v98, v98, v99
	v_cvt_pk_bf16_f32 v99, v100, v101
	v_max_f32_e32 v100, v102, v102
	v_max_f32_e32 v101, v103, v103
	v_max_f32_e32 v102, v104, v104
	v_max_f32_e32 v103, v105, v105
	v_cvt_pk_bf16_f32 v82, v82, v83
	v_cvt_pk_bf16_f32 v83, v84, v85
	v_max_f32_e32 v84, v86, v86
	v_max_f32_e32 v85, v87, v87
	v_max_f32_e32 v86, v88, v88
	v_max_f32_e32 v87, v89, v89
	v_cvt_pk_bf16_f32 v66, v66, v67
	v_cvt_pk_bf16_f32 v67, v68, v69
	v_max_f32_e32 v68, v70, v70
	v_max_f32_e32 v69, v71, v71
	v_max_f32_e32 v70, v72, v72
	v_max_f32_e32 v71, v73, v73
	v_cvt_pk_bf16_f32 v50, v50, v51
	v_cvt_pk_bf16_f32 v51, v52, v53
	v_max_f32_e32 v52, v54, v54
	v_max_f32_e32 v53, v55, v55
	v_max_f32_e32 v54, v56, v56
	v_max_f32_e32 v55, v57, v57
	v_cvt_pk_bf16_f32 v34, v34, v35
	v_cvt_pk_bf16_f32 v35, v36, v37
	v_max_f32_e32 v36, v38, v38
	v_max_f32_e32 v37, v39, v39
	v_max_f32_e32 v38, v40, v40
	v_max_f32_e32 v39, v41, v41
	v_cvt_pk_bf16_f32 v18, v18, v19
	v_cvt_pk_bf16_f32 v19, v20, v21
	v_max_f32_e32 v20, v22, v22
	v_max_f32_e32 v21, v23, v23
; __global__ void __launch_bounds__(512) mega(Params p) {
;     ...
; #pragma unroll
;         for (int tb = 0; tb < 2; ++tb)
; #pragma unroll
;           for (int fb = 0; fb < 4; ++fb)
; #pragma unroll
;             for (int jq = 0; jq < 4; ++jq) {
;               const f32x16& a = acc[tb * 4 + fb];
;               const float a0 = fmaxf(a[4 * jq], 0.f) * r2[tb], a1 = fmaxf(a[4 * jq + 1], 0.f) * r2[tb], a2 = fmaxf(a[4 * jq + 2], 0.f) * r2[tb], a3 = fmaxf(a[4 * jq + 3], 0.f) * r2[tb];
;               epi_put4(lds, wt * 64 + tb * 32 + l32, wf * 128 + fb * 32 + 8 * jq + 4 * hh, a0 * a0, a1 * a1, a2 * a2, a3 * a3);
;             }
	v_max_f32_e32 v22, v24, v24
	v_max_f32_e32 v23, v25, v25
	v_cvt_pk_bf16_f32 v2, v2, v3
	v_cvt_pk_bf16_f32 v3, v4, v5
	v_max_f32_e32 v4, v6, v6
	v_max_f32_e32 v5, v7, v7
	v_max_f32_e32 v6, v8, v8
	v_max_f32_e32 v7, v9, v9
	v_max_f32_e32 v116, 0, v116
	v_max_f32_e32 v117, 0, v117
	v_max_f32_e32 v118, 0, v118
	v_max_f32_e32 v119, 0, v119
	v_max_f32_e32 v100, 0, v100
	v_max_f32_e32 v101, 0, v101
	v_max_f32_e32 v102, 0, v102
	v_max_f32_e32 v103, 0, v103
	v_max_f32_e32 v84, 0, v84
	v_max_f32_e32 v85, 0, v85
	v_max_f32_e32 v86, 0, v86
	v_max_f32_e32 v87, 0, v87
	v_max_f32_e32 v68, 0, v68
	v_max_f32_e32 v69, 0, v69
	v_max_f32_e32 v70, 0, v70
	v_max_f32_e32 v71, 0, v71
	v_max_f32_e32 v52, 0, v52
	v_max_f32_e32 v53, 0, v53
	v_max_f32_e32 v54, 0, v54
	v_max_f32_e32 v55, 0, v55
	v_max_f32_e32 v36, 0, v36
	v_max_f32_e32 v37, 0, v37
	v_max_f32_e32 v38, 0, v38
	v_max_f32_e32 v39, 0, v39
	v_max_f32_e32 v20, 0, v20
	v_max_f32_e32 v21, 0, v21
	v_max_f32_e32 v22, 0, v22
	v_max_f32_e32 v23, 0, v23
	v_max_f32_e32 v4, 0, v4
	v_max_f32_e32 v5, 0, v5
	v_max_f32_e32 v6, 0, v6
	v_max_f32_e32 v7, 0, v7
	v_pk_mul_f32 v[116:117], v[138:139], v[116:117] op_sel_hi:[0,1]
	v_pk_mul_f32 v[118:119], v[138:139], v[118:119] op_sel_hi:[0,1]
	v_pk_mul_f32 v[100:101], v[138:139], v[100:101] op_sel_hi:[0,1]
	v_pk_mul_f32 v[102:103], v[138:139], v[102:103] op_sel_hi:[0,1]
	v_pk_mul_f32 v[84:85], v[138:139], v[84:85] op_sel_hi:[0,1]
	v_pk_mul_f32 v[86:87], v[138:139], v[86:87] op_sel_hi:[0,1]
	v_pk_mul_f32 v[68:69], v[138:139], v[68:69] op_sel_hi:[0,1]
	v_pk_mul_f32 v[70:71], v[138:139], v[70:71] op_sel_hi:[0,1]
	v_pk_mul_f32 v[52:53], v[0:1], v[52:53] op_sel_hi:[0,1]
	v_pk_mul_f32 v[54:55], v[0:1], v[54:55] op_sel_hi:[0,1]
	v_pk_mul_f32 v[36:37], v[0:1], v[36:37] op_sel_hi:[0,1]
	v_pk_mul_f32 v[38:39], v[0:1], v[38:39] op_sel_hi:[0,1]
	v_pk_mul_f32 v[20:21], v[0:1], v[20:21] op_sel_hi:[0,1]
	v_pk_mul_f32 v[22:23], v[0:1], v[22:23] op_sel_hi:[0,1]
	v_pk_mul_f32 v[4:5], v[0:1], v[4:5] op_sel_hi:[0,1]
	v_pk_mul_f32 v[6:7], v[0:1], v[6:7] op_sel_hi:[0,1]
	v_pk_mul_f32 v[116:117], v[116:117], v[116:117]
	v_pk_mul_f32 v[118:119], v[118:119], v[118:119]
	v_pk_mul_f32 v[100:101], v[100:101], v[100:101]
	v_pk_mul_f32 v[102:103], v[102:103], v[102:103]
	v_pk_mul_f32 v[84:85], v[84:85], v[84:85]
	v_pk_mul_f32 v[86:87], v[86:87], v[86:87]
	v_pk_mul_f32 v[68:69], v[68:69], v[68:69]
	v_pk_mul_f32 v[70:71], v[70:71], v[70:71]
	v_pk_mul_f32 v[52:53], v[52:53], v[52:53]
	v_pk_mul_f32 v[54:55], v[54:55], v[54:55]
	v_pk_mul_f32 v[36:37], v[36:37], v[36:37]
	v_pk_mul_f32 v[38:39], v[38:39], v[38:39]
	v_pk_mul_f32 v[20:21], v[20:21], v[20:21]
	v_pk_mul_f32 v[22:23], v[22:23], v[22:23]
	v_pk_mul_f32 v[4:5], v[4:5], v[4:5]
	v_pk_mul_f32 v[6:7], v[6:7], v[6:7]
	v_cvt_pk_bf16_f32 v116, v116, v117
	v_cvt_pk_bf16_f32 v117, v118, v119
	v_cvt_pk_bf16_f32 v100, v100, v101
	v_cvt_pk_bf16_f32 v101, v102, v103
	v_cvt_pk_bf16_f32 v84, v84, v85
	v_cvt_pk_bf16_f32 v85, v86, v87
	v_cvt_pk_bf16_f32 v68, v68, v69
	v_cvt_pk_bf16_f32 v69, v70, v71
	v_cvt_pk_bf16_f32 v52, v52, v53
	v_cvt_pk_bf16_f32 v53, v54, v55
	v_add_u32_e32 v56, 0x4000, v143
	v_cvt_pk_bf16_f32 v36, v36, v37
	v_cvt_pk_bf16_f32 v37, v38, v39
	v_cvt_pk_bf16_f32 v20, v20, v21
	v_cvt_pk_bf16_f32 v21, v22, v23
	v_cvt_pk_bf16_f32 v4, v4, v5
	v_cvt_pk_bf16_f32 v5, v6, v7
	ds_write2_b64 v143, v[114:115], v[116:117] offset1:2
	v_max_f32_e32 v114, v122, v122
	v_max_f32_e32 v115, v123, v123
	v_max_f32_e32 v116, v124, v124
	v_max_f32_e32 v117, v125, v125
	ds_write2_b64 v143, v[98:99], v[100:101] offset0:8 offset1:10
	v_max_f32_e32 v98, v106, v106
	v_max_f32_e32 v99, v107, v107
	v_max_f32_e32 v100, v108, v108
	v_max_f32_e32 v101, v109, v109
	ds_write2_b64 v143, v[82:83], v[84:85] offset0:16 offset1:18
	v_max_f32_e32 v82, v90, v90
	v_max_f32_e32 v83, v91, v91
	v_max_f32_e32 v84, v92, v92
	v_max_f32_e32 v85, v93, v93
	ds_write2_b64 v143, v[66:67], v[68:69] offset0:24 offset1:26
	v_max_f32_e32 v66, v74, v74
	v_max_f32_e32 v67, v75, v75
	v_max_f32_e32 v68, v76, v76
	v_max_f32_e32 v69, v77, v77
	ds_write2_b64 v56, v[50:51], v[52:53] offset0:64 offset1:66
	v_max_f32_e32 v50, v58, v58
	v_max_f32_e32 v51, v59, v59
	v_max_f32_e32 v52, v60, v60
	v_max_f32_e32 v53, v61, v61
	ds_write2_b64 v56, v[34:35], v[36:37] offset0:72 offset1:74
	v_max_f32_e32 v34, v42, v42
	v_max_f32_e32 v35, v43, v43
	v_max_f32_e32 v36, v44, v44
	v_max_f32_e32 v37, v45, v45
	ds_write2_b64 v56, v[18:19], v[20:21] offset0:80 offset1:82
	v_max_f32_e32 v18, v26, v26
	v_max_f32_e32 v19, v27, v27
	v_max_f32_e32 v20, v28, v28
	v_max_f32_e32 v21, v29, v29
	ds_write2_b64 v56, v[2:3], v[4:5] offset0:88 offset1:90
	v_max_f32_e32 v2, v10, v10
	v_max_f32_e32 v3, v11, v11
	v_max_f32_e32 v4, v12, v12
	v_max_f32_e32 v5, v13, v13
	v_max_f32_e32 v114, 0, v114
	v_max_f32_e32 v115, 0, v115
	v_max_f32_e32 v116, 0, v116
	v_max_f32_e32 v117, 0, v117
	v_max_f32_e32 v98, 0, v98
	v_max_f32_e32 v99, 0, v99
	v_max_f32_e32 v100, 0, v100
	v_max_f32_e32 v101, 0, v101
	v_max_f32_e32 v82, 0, v82
	v_max_f32_e32 v83, 0, v83
	v_max_f32_e32 v84, 0, v84
	v_max_f32_e32 v85, 0, v85
	v_max_f32_e32 v66, 0, v66
	v_max_f32_e32 v67, 0, v67
	v_max_f32_e32 v68, 0, v68
	v_max_f32_e32 v69, 0, v69
	v_max_f32_e32 v50, 0, v50
	v_max_f32_e32 v51, 0, v51
	v_max_f32_e32 v52, 0, v52
	v_max_f32_e32 v53, 0, v53
	v_max_f32_e32 v34, 0, v34
	v_max_f32_e32 v35, 0, v35
	v_max_f32_e32 v36, 0, v36
	v_max_f32_e32 v37, 0, v37
	v_max_f32_e32 v18, 0, v18
	v_max_f32_e32 v19, 0, v19
	v_max_f32_e32 v20, 0, v20
	v_max_f32_e32 v21, 0, v21
	v_max_f32_e32 v2, 0, v2
	v_max_f32_e32 v3, 0, v3
	v_max_f32_e32 v4, 0, v4
	v_max_f32_e32 v5, 0, v5
; __global__ void __launch_bounds__(512) mega(Params p) {
;     ...
; #pragma unroll
;         for (int tb = 0; tb < 2; ++tb)
; #pragma unroll
;           for (int fb = 0; fb < 4; ++fb)
; #pragma unroll
;             for (int jq = 0; jq < 4; ++jq) {
;               const f32x16& a = acc[tb * 4 + fb];
;               const float a0 = fmaxf(a[4 * jq], 0.f) * r2[tb], a1 = fmaxf(a[4 * jq + 1], 0.f) * r2[tb], a2 = fmaxf(a[4 * jq + 2], 0.f) * r2[tb], a3 = fmaxf(a[4 * jq + 3], 0.f) * r2[tb];
;               epi_put4(lds, wt * 64 + tb * 32 + l32, wf * 128 + fb * 32 + 8 * jq + 4 * hh, a0 * a0, a1 * a1, a2 * a2, a3 * a3);
;             }
	v_pk_mul_f32 v[114:115], v[138:139], v[114:115] op_sel_hi:[0,1]
	v_pk_mul_f32 v[116:117], v[138:139], v[116:117] op_sel_hi:[0,1]
	v_pk_mul_f32 v[98:99], v[138:139], v[98:99] op_sel_hi:[0,1]
	v_pk_mul_f32 v[100:101], v[138:139], v[100:101] op_sel_hi:[0,1]
	v_pk_mul_f32 v[82:83], v[138:139], v[82:83] op_sel_hi:[0,1]
	v_pk_mul_f32 v[84:85], v[138:139], v[84:85] op_sel_hi:[0,1]
	v_pk_mul_f32 v[66:67], v[138:139], v[66:67] op_sel_hi:[0,1]
	v_pk_mul_f32 v[68:69], v[138:139], v[68:69] op_sel_hi:[0,1]
	v_pk_mul_f32 v[50:51], v[0:1], v[50:51] op_sel_hi:[0,1]
	v_pk_mul_f32 v[52:53], v[0:1], v[52:53] op_sel_hi:[0,1]
	v_pk_mul_f32 v[34:35], v[0:1], v[34:35] op_sel_hi:[0,1]
	v_pk_mul_f32 v[36:37], v[0:1], v[36:37] op_sel_hi:[0,1]
	v_pk_mul_f32 v[18:19], v[0:1], v[18:19] op_sel_hi:[0,1]
	v_pk_mul_f32 v[20:21], v[0:1], v[20:21] op_sel_hi:[0,1]
	v_pk_mul_f32 v[2:3], v[0:1], v[2:3] op_sel_hi:[0,1]
	v_pk_mul_f32 v[4:5], v[0:1], v[4:5] op_sel_hi:[0,1]
	v_pk_mul_f32 v[114:115], v[114:115], v[114:115]
	v_pk_mul_f32 v[116:117], v[116:117], v[116:117]
	v_pk_mul_f32 v[98:99], v[98:99], v[98:99]
	v_pk_mul_f32 v[100:101], v[100:101], v[100:101]
	v_pk_mul_f32 v[82:83], v[82:83], v[82:83]
	v_pk_mul_f32 v[84:85], v[84:85], v[84:85]
	v_pk_mul_f32 v[66:67], v[66:67], v[66:67]
	v_pk_mul_f32 v[68:69], v[68:69], v[68:69]
	v_pk_mul_f32 v[50:51], v[50:51], v[50:51]
	v_pk_mul_f32 v[52:53], v[52:53], v[52:53]
	v_pk_mul_f32 v[34:35], v[34:35], v[34:35]
	v_pk_mul_f32 v[36:37], v[36:37], v[36:37]
	v_pk_mul_f32 v[18:19], v[18:19], v[18:19]
	v_pk_mul_f32 v[20:21], v[20:21], v[20:21]
	v_pk_mul_f32 v[2:3], v[2:3], v[2:3]
	v_pk_mul_f32 v[4:5], v[4:5], v[4:5]
	v_cvt_pk_bf16_f32 v114, v114, v115
	v_cvt_pk_bf16_f32 v115, v116, v117
	v_max_f32_e32 v116, v126, v126
	v_max_f32_e32 v117, v127, v127
	v_max_f32_e32 v118, v128, v128
	v_max_f32_e32 v119, v129, v129
	v_cvt_pk_bf16_f32 v98, v98, v99
	v_cvt_pk_bf16_f32 v99, v100, v101
	v_max_f32_e32 v100, v110, v110
	v_max_f32_e32 v101, v111, v111
	v_max_f32_e32 v102, v112, v112
	v_max_f32_e32 v103, v113, v113
	v_cvt_pk_bf16_f32 v82, v82, v83
	v_cvt_pk_bf16_f32 v83, v84, v85
	v_max_f32_e32 v84, v94, v94
	v_max_f32_e32 v85, v95, v95
	v_max_f32_e32 v86, v96, v96
	v_max_f32_e32 v87, v97, v97
	v_cvt_pk_bf16_f32 v66, v66, v67
	v_cvt_pk_bf16_f32 v67, v68, v69
	v_max_f32_e32 v68, v78, v78
	v_max_f32_e32 v69, v79, v79
	v_max_f32_e32 v70, v80, v80
	v_max_f32_e32 v71, v81, v81
	v_cvt_pk_bf16_f32 v50, v50, v51
	v_cvt_pk_bf16_f32 v51, v52, v53
	v_max_f32_e32 v52, v62, v62
	v_max_f32_e32 v53, v63, v63
	v_max_f32_e32 v54, v64, v64
	v_max_f32_e32 v55, v65, v65
	v_cvt_pk_bf16_f32 v34, v34, v35
	v_cvt_pk_bf16_f32 v35, v36, v37
	v_max_f32_e32 v36, v46, v46
	v_max_f32_e32 v37, v47, v47
	v_max_f32_e32 v38, v48, v48
	v_max_f32_e32 v39, v49, v49
	v_cvt_pk_bf16_f32 v18, v18, v19
	v_cvt_pk_bf16_f32 v19, v20, v21
	v_max_f32_e32 v20, v30, v30
	v_max_f32_e32 v21, v31, v31
	v_max_f32_e32 v22, v32, v32
	v_max_f32_e32 v23, v33, v33
	v_cvt_pk_bf16_f32 v2, v2, v3
	v_cvt_pk_bf16_f32 v3, v4, v5
	v_max_f32_e32 v4, v14, v14
	v_max_f32_e32 v5, v15, v15
	v_max_f32_e32 v6, v16, v16
	v_max_f32_e32 v7, v17, v17
	v_max_f32_e32 v116, 0, v116
	v_max_f32_e32 v117, 0, v117
	v_max_f32_e32 v118, 0, v118
	v_max_f32_e32 v119, 0, v119
	v_max_f32_e32 v100, 0, v100
	v_max_f32_e32 v101, 0, v101
	v_max_f32_e32 v102, 0, v102
	v_max_f32_e32 v103, 0, v103
	v_max_f32_e32 v84, 0, v84
	v_max_f32_e32 v85, 0, v85
	v_max_f32_e32 v86, 0, v86
	v_max_f32_e32 v87, 0, v87
	v_max_f32_e32 v68, 0, v68
	v_max_f32_e32 v69, 0, v69
	v_max_f32_e32 v70, 0, v70
	v_max_f32_e32 v71, 0, v71
	v_max_f32_e32 v52, 0, v52
	v_max_f32_e32 v53, 0, v53
	v_max_f32_e32 v54, 0, v54
	v_max_f32_e32 v55, 0, v55
	v_max_f32_e32 v36, 0, v36
	v_max_f32_e32 v37, 0, v37
	v_max_f32_e32 v38, 0, v38
	v_max_f32_e32 v39, 0, v39
	v_max_f32_e32 v20, 0, v20
	v_max_f32_e32 v21, 0, v21
	v_max_f32_e32 v22, 0, v22
	v_max_f32_e32 v23, 0, v23
	v_max_f32_e32 v4, 0, v4
	v_max_f32_e32 v5, 0, v5
	v_max_f32_e32 v6, 0, v6
	v_max_f32_e32 v7, 0, v7
	v_pk_mul_f32 v[116:117], v[138:139], v[116:117] op_sel_hi:[0,1]
	v_pk_mul_f32 v[118:119], v[138:139], v[118:119] op_sel_hi:[0,1]
	v_pk_mul_f32 v[100:101], v[138:139], v[100:101] op_sel_hi:[0,1]
	v_pk_mul_f32 v[102:103], v[138:139], v[102:103] op_sel_hi:[0,1]
	v_pk_mul_f32 v[84:85], v[138:139], v[84:85] op_sel_hi:[0,1]
	v_pk_mul_f32 v[86:87], v[138:139], v[86:87] op_sel_hi:[0,1]
	v_pk_mul_f32 v[68:69], v[138:139], v[68:69] op_sel_hi:[0,1]
	v_pk_mul_f32 v[70:71], v[138:139], v[70:71] op_sel_hi:[0,1]
	v_pk_mul_f32 v[52:53], v[0:1], v[52:53] op_sel_hi:[0,1]
	v_pk_mul_f32 v[54:55], v[0:1], v[54:55] op_sel_hi:[0,1]
	v_pk_mul_f32 v[36:37], v[0:1], v[36:37] op_sel_hi:[0,1]
	v_pk_mul_f32 v[38:39], v[0:1], v[38:39] op_sel_hi:[0,1]
	v_pk_mul_f32 v[20:21], v[0:1], v[20:21] op_sel_hi:[0,1]
	v_pk_mul_f32 v[22:23], v[0:1], v[22:23] op_sel_hi:[0,1]
	v_pk_mul_f32 v[4:5], v[0:1], v[4:5] op_sel_hi:[0,1]
	v_pk_mul_f32 v[6:7], v[0:1], v[6:7] op_sel_hi:[0,1]
	v_pk_mul_f32 v[116:117], v[116:117], v[116:117]
	v_pk_mul_f32 v[118:119], v[118:119], v[118:119]
	v_pk_mul_f32 v[100:101], v[100:101], v[100:101]
	v_pk_mul_f32 v[102:103], v[102:103], v[102:103]
	v_pk_mul_f32 v[84:85], v[84:85], v[84:85]
	v_pk_mul_f32 v[86:87], v[86:87], v[86:87]
	v_pk_mul_f32 v[68:69], v[68:69], v[68:69]
	v_pk_mul_f32 v[70:71], v[70:71], v[70:71]
	v_pk_mul_f32 v[52:53], v[52:53], v[52:53]
	v_pk_mul_f32 v[54:55], v[54:55], v[54:55]
	v_pk_mul_f32 v[36:37], v[36:37], v[36:37]
	v_pk_mul_f32 v[38:39], v[38:39], v[38:39]
	v_pk_mul_f32 v[20:21], v[20:21], v[20:21]
	v_pk_mul_f32 v[22:23], v[22:23], v[22:23]
	v_pk_mul_f32 v[4:5], v[4:5], v[4:5]
	v_pk_mul_f32 v[6:7], v[6:7], v[6:7]
	v_cvt_pk_bf16_f32 v116, v116, v117
	v_cvt_pk_bf16_f32 v117, v118, v119
	v_cvt_pk_bf16_f32 v100, v100, v101
	v_cvt_pk_bf16_f32 v101, v102, v103
	v_cvt_pk_bf16_f32 v84, v84, v85
	v_cvt_pk_bf16_f32 v85, v86, v87
	v_cvt_pk_bf16_f32 v68, v68, v69
	v_cvt_pk_bf16_f32 v69, v70, v71
	v_cvt_pk_bf16_f32 v52, v52, v53
	v_cvt_pk_bf16_f32 v53, v54, v55
	v_cvt_pk_bf16_f32 v36, v36, v37
	v_cvt_pk_bf16_f32 v37, v38, v39
	v_cvt_pk_bf16_f32 v20, v20, v21
	v_cvt_pk_bf16_f32 v21, v22, v23
	v_cvt_pk_bf16_f32 v4, v4, v5
	v_cvt_pk_bf16_f32 v5, v6, v7
	ds_write2_b64 v143, v[114:115], v[116:117] offset0:4 offset1:6
	ds_write2_b64 v143, v[98:99], v[100:101] offset0:12 offset1:14
	ds_write2_b64 v143, v[82:83], v[84:85] offset0:20 offset1:22
	ds_write2_b64 v143, v[66:67], v[68:69] offset0:28 offset1:30
	ds_write2_b64 v56, v[50:51], v[52:53] offset0:68 offset1:70
	ds_write2_b64 v56, v[34:35], v[36:37] offset0:76 offset1:78
	ds_write2_b64 v56, v[18:19], v[20:21] offset0:84 offset1:86
	ds_write2_b64 v56, v[2:3], v[4:5] offset0:92 offset1:94
	s_waitcnt lgkmcnt(0)
	s_barrier
; __global__ void __launch_bounds__(512) mega(Params p) {
;     ...
;         {
;           const int r0 = tid >> 5, ch = tid & 31;
;           u16* ub = (u16*)(ws + R_U) + ((size_t)(tt * 64 + ft * 4 + (ch >> 3)) * 256) * 64 + (ch & 7) * 8;
;           __syncthreads();
; #pragma unroll 4
;           for (int r = r0; r < 256; r += 16) __builtin_nontemporal_store(*(const u32x4*)(lds + r * EROW + ch * 16), (u32x4*)(ub + (size_t)r * 64));
	s_and_saveexec_b64 s[10:11], vcc
	s_cbranch_execz .LBB0_147
	v_mov_b32_e32 v10, v130
	s_and_saveexec_b64 s[8:9], s[0:1]
	s_cbranch_execz .LBB0_155
	s_lshl_b32 s7, s59, 4
	s_lshl_b32 s33, s66, 2
	s_lshl_b32 s6, s64, 6
	s_add_i32 s7, s33, s7
	s_add_i32 s7, s7, s6
	v_or_b32_e32 v2, s7, v142
	v_ashrrev_i32_e32 v3, 31, v2
	v_lshlrev_b64 v[2:3], 15, v[2:3]
	v_lshl_add_u64 v[2:3], v[134:135], 0, v[2:3]
	s_mov_b64 s[34:35], 0
	v_mov_b32_e32 v0, v148
	v_mov_b32_e32 v4, v131
	v_mov_b32_e32 v10, v130
	s_mov_b64 s[68:69], 0x800

; DI f32x16 mfma(bf16x8 a, bf16x8 b, f32x16 c) { return __builtin_amdgcn_mfma_f32_32x32x16_bf16(a, b, c, 0, 0, 0); }
;     ...
;   __syncthreads();
;   DMA_ISSUE(0, 0)
;   asm volatile("s_waitcnt vmcnt(0)" ::: "memory");
;   __builtin_amdgcn_s_barrier();
;   for (int kt = 0; kt < nk; ++kt) {
;     const char* cur = lds + (kt & 1) * DBUF;
;     if (kt + 1 < nk) DMA_ISSUE((kt + 1) & 1, kt + 1)
; #pragma unroll(NTB == 1 ? 2 : 4)
;     for (int s = 0; s < 4; ++s) {
;       const int ro = ((2 * s + hh) ^ xr) * 16;
;       bf16x8 bfr[NTB];
; #pragma unroll
;       for (int tb = 0; tb < NTB; ++tb) bfr[tb] = *(const bf16x8*)(cur + bbase + tb * 32 * DROW + ro);
; #pragma unroll
;       for (int fb = 0; fb < NFB; ++fb) {
;         const bf16x8 afr = *(const bf16x8*)(cur + abase + fb * 32 * DROW + ro);
; #pragma unroll
;         for (int tb = 0; tb < NTB; ++tb) acc[tb * NFB + fb] = mfma(afr, bfr[tb], acc[tb * NFB + fb]);
;       }
;     }
;     asm volatile("s_waitcnt vmcnt(0) lgkmcnt(0)" ::: "memory");
;     __builtin_amdgcn_s_barrier();
;   }
.LBB0_170:
	s_add_i32 s8, s5, 0xffff0000
	s_and_b32 s8, s8, 0x10000
	v_add_u32_e32 v184, s8, v143
	v_add_u32_e32 v186, s8, v149
	v_add_u32_e32 v189, v184, v148
	v_add_u32_e32 v194, v186, v148
	ds_read_b128 v[234:237], v189 offset:32768
	ds_read_b128 v[238:241], v189 offset:36864
	ds_read_b128 v[250:253], v194
	ds_read_b128 v[180:183], v194 offset:4096
	ds_read_b128 v[190:193], v194 offset:8192
	ds_read_b128 v[158:161], v194 offset:12288
	v_add_u32_e32 v189, v184, v141
	v_add_u32_e32 v194, v186, v141
	ds_read_b128 v[242:245], v189 offset:32768
	ds_read_b128 v[246:249], v189 offset:36864
	s_waitcnt lgkmcnt(5)
	v_mfma_f32_32x32x16_bf16 v[114:129], v[250:253], v[234:237], v[114:129]
	v_mfma_f32_32x32x16_bf16 v[50:65], v[250:253], v[238:241], v[50:65]
	ds_read_b128 v[250:253], v194
	s_and_b32 s9, s5, 0x10000
	v_add_u32_e32 v154, s9, v142
	v_lshl_add_u64 v[150:151], v[134:135], 0, s[66:67]
	v_readfirstlane_b32 s9, v154
	v_add_u32_e32 v155, 0x2000, v154
	v_lshl_add_u64 v[152:153], v[150:151], 0, s[56:57]
	s_mov_b32 m0, s9
	v_readfirstlane_b32 s9, v155
	v_add_u32_e32 v155, 0x4000, v154
	global_load_lds_dwordx4 v[152:153], off
	s_waitcnt lgkmcnt(5)
	v_mfma_f32_32x32x16_bf16 v[98:113], v[180:183], v[234:237], v[98:113]
	v_mfma_f32_32x32x16_bf16 v[34:49], v[180:183], v[238:241], v[34:49]
	ds_read_b128 v[180:183], v194 offset:4096
	v_lshl_add_u64 v[152:153], v[150:151], 0, s[68:69]
	s_mov_b32 m0, s9
	v_readfirstlane_b32 s9, v155
	global_load_lds_dwordx4 v[152:153], off
	s_waitcnt lgkmcnt(5)
	v_mfma_f32_32x32x16_bf16 v[82:97], v[190:193], v[234:237], v[82:97]
	v_mfma_f32_32x32x16_bf16 v[18:33], v[190:193], v[238:241], v[18:33]
	ds_read_b128 v[190:193], v194 offset:8192
	v_lshl_add_u64 v[152:153], v[150:151], 0, s[58:59]
	s_mov_b32 m0, s9
	v_lshl_add_u64 v[150:151], v[150:151], 0, s[70:71]
	global_load_lds_dwordx4 v[152:153], off
	s_waitcnt lgkmcnt(5)
	v_mfma_f32_32x32x16_bf16 v[66:81], v[158:161], v[234:237], v[66:81]
	v_mfma_f32_32x32x16_bf16 v[2:17], v[158:161], v[238:241], v[2:17]
	ds_read_b128 v[158:161], v194 offset:12288
	v_add_u32_e32 v152, 0x6000, v154
	v_add_u32_e32 v155, 0x8000, v154
	v_readfirstlane_b32 s9, v152
	s_mov_b32 m0, s9
	v_readfirstlane_b32 s9, v155
	global_load_lds_dwordx4 v[150:151], off
	v_add_u32_e32 v189, v184, v140
	v_add_u32_e32 v194, v186, v140
	ds_read_b128 v[234:237], v189 offset:32768
	ds_read_b128 v[238:241], v189 offset:36864
	s_waitcnt lgkmcnt(5)
	v_mfma_f32_32x32x16_bf16 v[114:129], v[250:253], v[242:245], v[114:129]
	v_mfma_f32_32x32x16_bf16 v[50:65], v[250:253], v[246:249], v[50:65]
	ds_read_b128 v[250:253], v194
	v_lshl_add_u64 v[150:151], v[136:137], 0, s[66:67]
	v_add_u32_e32 v155, 0xa000, v154
	v_lshl_add_u64 v[152:153], v[150:151], 0, s[56:57]
	s_mov_b32 m0, s9
	v_readfirstlane_b32 s9, v155
	v_add_u32_e32 v155, 0xc000, v154
	global_load_lds_dwordx4 v[152:153], off
	s_waitcnt lgkmcnt(5)
	v_mfma_f32_32x32x16_bf16 v[98:113], v[180:183], v[242:245], v[98:113]
	v_mfma_f32_32x32x16_bf16 v[34:49], v[180:183], v[246:249], v[34:49]
	ds_read_b128 v[180:183], v194 offset:4096
	v_lshl_add_u64 v[152:153], v[150:151], 0, s[68:69]
	s_mov_b32 m0, s9
	v_readfirstlane_b32 s9, v155
	s_add_i32 s8, s5, 0xffff0000
	global_load_lds_dwordx4 v[152:153], off
	s_waitcnt lgkmcnt(5)
	v_mfma_f32_32x32x16_bf16 v[82:97], v[190:193], v[242:245], v[82:97]
	v_mfma_f32_32x32x16_bf16 v[18:33], v[190:193], v[246:249], v[18:33]
	ds_read_b128 v[190:193], v194 offset:8192
	v_lshl_add_u64 v[152:153], v[150:151], 0, s[58:59]
	s_mov_b32 m0, s9
	s_and_b32 s8, s8, 0x10000
	global_load_lds_dwordx4 v[152:153], off
	s_waitcnt lgkmcnt(5)
	v_mfma_f32_32x32x16_bf16 v[66:81], v[158:161], v[242:245], v[66:81]
	v_mfma_f32_32x32x16_bf16 v[2:17], v[158:161], v[246:249], v[2:17]
	ds_read_b128 v[158:161], v194 offset:12288
	v_add_u32_e32 v152, 0xe000, v154
	s_add_i32 s8, s8, 0
	v_readfirstlane_b32 s9, v152
	v_lshl_add_u64 v[150:151], v[150:151], 0, s[70:71]
	s_mov_b32 m0, s9
	v_add_u32_e32 v162, s8, v143
	v_add_u32_e32 v163, s8, v149
	global_load_lds_dwordx4 v[150:151], off
	v_add_u32_e32 v189, v184, v0
	v_add_u32_e32 v194, v186, v0
	ds_read_b128 v[242:245], v189 offset:32768
	ds_read_b128 v[246:249], v189 offset:36864
	s_waitcnt lgkmcnt(5)
	v_mfma_f32_32x32x16_bf16 v[114:129], v[250:253], v[234:237], v[114:129]
	v_mfma_f32_32x32x16_bf16 v[50:65], v[250:253], v[238:241], v[50:65]
	ds_read_b128 v[250:253], v194
	s_add_u32 s66, s66, 0x8000
	s_addc_u32 s67, s67, 0
	s_add_i32 s5, s5, 0x10000
	s_cmp_eq_u32 s66, 0x1f8000
	s_waitcnt lgkmcnt(5)
	v_mfma_f32_32x32x16_bf16 v[98:113], v[180:183], v[234:237], v[98:113]
	v_mfma_f32_32x32x16_bf16 v[34:49], v[180:183], v[238:241], v[34:49]
	ds_read_b128 v[180:183], v194 offset:4096
	s_waitcnt lgkmcnt(5)
	v_mfma_f32_32x32x16_bf16 v[82:97], v[190:193], v[234:237], v[82:97]
	v_mfma_f32_32x32x16_bf16 v[18:33], v[190:193], v[238:241], v[18:33]
	ds_read_b128 v[190:193], v194 offset:8192
	s_waitcnt lgkmcnt(5)
	v_mfma_f32_32x32x16_bf16 v[66:81], v[158:161], v[234:237], v[66:81]
	v_mfma_f32_32x32x16_bf16 v[2:17], v[158:161], v[238:241], v[2:17]
	ds_read_b128 v[158:161], v194 offset:12288
	s_waitcnt lgkmcnt(3)
	v_mfma_f32_32x32x16_bf16 v[114:129], v[250:253], v[242:245], v[114:129]
	v_mfma_f32_32x32x16_bf16 v[50:65], v[250:253], v[246:249], v[50:65]
	s_waitcnt lgkmcnt(2)
	v_mfma_f32_32x32x16_bf16 v[98:113], v[180:183], v[242:245], v[98:113]
	v_mfma_f32_32x32x16_bf16 v[34:49], v[180:183], v[246:249], v[34:49]
	s_waitcnt lgkmcnt(1)
	v_mfma_f32_32x32x16_bf16 v[82:97], v[190:193], v[242:245], v[82:97]
	v_mfma_f32_32x32x16_bf16 v[18:33], v[190:193], v[246:249], v[18:33]
	s_waitcnt vmcnt(0) lgkmcnt(0)
	s_barrier
; DI f32x16 mfma(bf16x8 a, bf16x8 b, f32x16 c) { return __builtin_amdgcn_mfma_f32_32x32x16_bf16(a, b, c, 0, 0, 0); }
;     ...
;   for (int kt = 0; kt < nk; ++kt) {
;     const char* cur = lds + (kt & 1) * DBUF;
;     if (kt + 1 < nk) DMA_ISSUE((kt + 1) & 1, kt + 1)
; #pragma unroll(NTB == 1 ? 2 : 4)
;     for (int s = 0; s < 4; ++s) {
;       const int ro = ((2 * s + hh) ^ xr) * 16;
;       bf16x8 bfr[NTB];
; #pragma unroll
;       for (int tb = 0; tb < NTB; ++tb) bfr[tb] = *(const bf16x8*)(cur + bbase + tb * 32 * DROW + ro);
; #pragma unroll
;       for (int fb = 0; fb < NFB; ++fb) {
;         const bf16x8 afr = *(const bf16x8*)(cur + abase + fb * 32 * DROW + ro);
; #pragma unroll
;         for (int tb = 0; tb < NTB; ++tb) acc[tb * NFB + fb] = mfma(afr, bfr[tb], acc[tb * NFB + fb]);
;       }
;     }
;     asm volatile("s_waitcnt vmcnt(0) lgkmcnt(0)" ::: "memory");
;     __builtin_amdgcn_s_barrier();
;   }
	v_mfma_f32_32x32x16_bf16 v[66:81], v[158:161], v[242:245], v[66:81]
	v_mfma_f32_32x32x16_bf16 v[2:17], v[158:161], v[246:249], v[2:17]
	s_cbranch_scc0 .LBB0_170
	s_add_i32 s5, 0, 0x10000
	v_add_u32_e32 v158, s5, v143
	v_add_u32_e32 v159, s5, v149
	v_add_u32_e32 v142, v158, v148
	ds_read_b128 v[134:137], v142 offset:32768
	ds_read_b128 v[150:153], v142 offset:36864
	v_add_u32_e32 v142, v159, v148
	ds_read_b128 v[154:157], v142
	s_mov_b64 s[8:9], 0
	s_waitcnt lgkmcnt(0)
	v_mfma_f32_32x32x16_bf16 v[114:129], v[154:157], v[134:137], v[114:129]
	v_mfma_f32_32x32x16_bf16 v[50:65], v[154:157], v[150:153], v[50:65]
	ds_read_b128 v[154:157], v142 offset:4096
	s_waitcnt lgkmcnt(0)
	v_mfma_f32_32x32x16_bf16 v[98:113], v[154:157], v[134:137], v[98:113]
	v_mfma_f32_32x32x16_bf16 v[34:49], v[154:157], v[150:153], v[34:49]
	ds_read_b128 v[154:157], v142 offset:8192
	s_waitcnt lgkmcnt(0)
	v_mfma_f32_32x32x16_bf16 v[82:97], v[154:157], v[134:137], v[82:97]
	v_mfma_f32_32x32x16_bf16 v[18:33], v[154:157], v[150:153], v[18:33]
	ds_read_b128 v[154:157], v142 offset:12288
	v_add_u32_e32 v142, v158, v141
	v_add_u32_e32 v141, v159, v141
	s_waitcnt lgkmcnt(0)
	v_mfma_f32_32x32x16_bf16 v[66:81], v[154:157], v[134:137], v[66:81]
	v_mfma_f32_32x32x16_bf16 v[2:17], v[154:157], v[150:153], v[2:17]
	ds_read_b128 v[134:137], v142 offset:32768
	ds_read_b128 v[148:151], v142 offset:36864
	ds_read_b128 v[152:155], v141
	s_waitcnt lgkmcnt(0)
	v_mfma_f32_32x32x16_bf16 v[114:129], v[152:155], v[134:137], v[114:129]
	v_mfma_f32_32x32x16_bf16 v[50:65], v[152:155], v[148:151], v[50:65]
	ds_read_b128 v[152:155], v141 offset:4096
	s_waitcnt lgkmcnt(0)
	v_mfma_f32_32x32x16_bf16 v[98:113], v[152:155], v[134:137], v[98:113]
	v_mfma_f32_32x32x16_bf16 v[34:49], v[152:155], v[148:151], v[34:49]
	ds_read_b128 v[152:155], v141 offset:8192
	s_waitcnt lgkmcnt(0)
	v_mfma_f32_32x32x16_bf16 v[82:97], v[152:155], v[134:137], v[82:97]
	v_mfma_f32_32x32x16_bf16 v[18:33], v[152:155], v[148:151], v[18:33]
	ds_read_b128 v[152:155], v141 offset:12288
	v_add_u32_e32 v141, v158, v140
	s_waitcnt lgkmcnt(0)
	v_mfma_f32_32x32x16_bf16 v[66:81], v[152:155], v[134:137], v[66:81]
	v_mfma_f32_32x32x16_bf16 v[2:17], v[152:155], v[148:151], v[2:17]
	v_add_u32_e32 v152, v159, v140
	ds_read_b128 v[134:137], v141 offset:32768
	ds_read_b128 v[148:151], v141 offset:36864
	ds_read_b128 v[140:143], v152
	s_waitcnt lgkmcnt(0)
	v_mfma_f32_32x32x16_bf16 v[114:129], v[140:143], v[134:137], v[114:129]
	v_mfma_f32_32x32x16_bf16 v[50:65], v[140:143], v[148:151], v[50:65]
	ds_read_b128 v[140:143], v152 offset:4096
	s_waitcnt lgkmcnt(0)
	v_mfma_f32_32x32x16_bf16 v[98:113], v[140:143], v[134:137], v[98:113]
	v_mfma_f32_32x32x16_bf16 v[34:49], v[140:143], v[148:151], v[34:49]
	ds_read_b128 v[140:143], v152 offset:8192
	s_waitcnt lgkmcnt(0)
	v_mfma_f32_32x32x16_bf16 v[82:97], v[140:143], v[134:137], v[82:97]
	v_mfma_f32_32x32x16_bf16 v[18:33], v[140:143], v[148:151], v[18:33]
	ds_read_b128 v[140:143], v152 offset:12288
	s_waitcnt lgkmcnt(0)
	v_mfma_f32_32x32x16_bf16 v[66:81], v[140:143], v[134:137], v[66:81]
	v_mfma_f32_32x32x16_bf16 v[2:17], v[140:143], v[148:151], v[2:17]
	v_add_u32_e32 v140, v158, v0
	v_add_u32_e32 v0, v159, v0
	ds_read_b128 v[134:137], v140 offset:32768
	ds_read_b128 v[140:143], v140 offset:36864
	ds_read_b128 v[148:151], v0
	s_waitcnt lgkmcnt(0)
	v_mfma_f32_32x32x16_bf16 v[114:129], v[148:151], v[134:137], v[114:129]
	v_mfma_f32_32x32x16_bf16 v[50:65], v[148:151], v[140:143], v[50:65]
	ds_read_b128 v[148:151], v0 offset:4096
	s_waitcnt lgkmcnt(0)
	v_mfma_f32_32x32x16_bf16 v[98:113], v[148:151], v[134:137], v[98:113]
	v_mfma_f32_32x32x16_bf16 v[34:49], v[148:151], v[140:143], v[34:49]
	ds_read_b128 v[148:151], v0 offset:8192
	s_waitcnt lgkmcnt(0)
	v_mfma_f32_32x32x16_bf16 v[82:97], v[148:151], v[134:137], v[82:97]
	v_mfma_f32_32x32x16_bf16 v[18:33], v[148:151], v[140:143], v[18:33]
	ds_read_b128 v[148:151], v0 offset:12288
	s_waitcnt vmcnt(0) lgkmcnt(0)
	s_barrier
	s_waitcnt lgkmcnt(0)
	v_mfma_f32_32x32x16_bf16 v[66:81], v[148:151], v[134:137], v[66:81]
	v_mfma_f32_32x32x16_bf16 v[2:17], v[148:151], v[140:143], v[2:17]

; DI f32x16 mfma(bf16x8 a, bf16x8 b, f32x16 c) { return __builtin_amdgcn_mfma_f32_32x32x16_bf16(a, b, c, 0, 0, 0); }
;     ...
;   __syncthreads();
;   DMA_ISSUE(0, 0)
;   asm volatile("s_waitcnt vmcnt(0)" ::: "memory");
;   __builtin_amdgcn_s_barrier();
;   for (int kt = 0; kt < nk; ++kt) {
;     const char* cur = lds + (kt & 1) * DBUF;
;     if (kt + 1 < nk) DMA_ISSUE((kt + 1) & 1, kt + 1)
; #pragma unroll(NTB == 1 ? 2 : 4)
;     for (int s = 0; s < 4; ++s) {
;       const int ro = ((2 * s + hh) ^ xr) * 16;
;       bf16x8 bfr[NTB];
; #pragma unroll
;       for (int tb = 0; tb < NTB; ++tb) bfr[tb] = *(const bf16x8*)(cur + bbase + tb * 32 * DROW + ro);
; #pragma unroll
;       for (int fb = 0; fb < NFB; ++fb) {
;         const bf16x8 afr = *(const bf16x8*)(cur + abase + fb * 32 * DROW + ro);
; #pragma unroll
;         for (int tb = 0; tb < NTB; ++tb) acc[tb * NFB + fb] = mfma(afr, bfr[tb], acc[tb * NFB + fb]);
;       }
;     }
;     asm volatile("s_waitcnt vmcnt(0) lgkmcnt(0)" ::: "memory");
;     __builtin_amdgcn_s_barrier();
;   }
.LBB0_174:
	s_add_i32 s8, s5, 0xffff0000
	s_and_b32 s8, s8, 0x10000
	v_add_u32_e32 v184, s8, v143
	v_add_u32_e32 v186, s8, v149
	v_add_u32_e32 v189, v184, v148
	v_add_u32_e32 v194, v186, v148
	ds_read_b128 v[234:237], v189 offset:32768
	ds_read_b128 v[238:241], v189 offset:36864
	ds_read_b128 v[250:253], v194
	ds_read_b128 v[180:183], v194 offset:4096
	ds_read_b128 v[190:193], v194 offset:8192
	ds_read_b128 v[158:161], v194 offset:12288
	v_add_u32_e32 v189, v184, v141
	v_add_u32_e32 v194, v186, v141
	ds_read_b128 v[242:245], v189 offset:32768
	ds_read_b128 v[246:249], v189 offset:36864
	s_waitcnt lgkmcnt(5)
	v_mfma_f32_32x32x16_bf16 v[114:129], v[250:253], v[234:237], v[114:129]
	v_mfma_f32_32x32x16_bf16 v[50:65], v[250:253], v[238:241], v[50:65]
	ds_read_b128 v[250:253], v194
	s_and_b32 s9, s5, 0x10000
	v_add_u32_e32 v154, s9, v142
	v_lshl_add_u64 v[150:151], v[134:135], 0, s[34:35]
	v_readfirstlane_b32 s9, v154
	v_add_u32_e32 v155, 0x2000, v154
	v_lshl_add_u64 v[152:153], v[150:151], 0, s[84:85]
	s_mov_b32 m0, s9
	v_readfirstlane_b32 s9, v155
	v_add_u32_e32 v155, 0x4000, v154
	global_load_lds_dwordx4 v[152:153], off
	s_waitcnt lgkmcnt(5)
	v_mfma_f32_32x32x16_bf16 v[98:113], v[180:183], v[234:237], v[98:113]
	v_mfma_f32_32x32x16_bf16 v[34:49], v[180:183], v[238:241], v[34:49]
	ds_read_b128 v[180:183], v194 offset:4096
	v_lshl_add_u64 v[152:153], v[150:151], 0, s[90:91]
	s_mov_b32 m0, s9
	v_readfirstlane_b32 s9, v155
	global_load_lds_dwordx4 v[152:153], off
	s_waitcnt lgkmcnt(5)
	v_mfma_f32_32x32x16_bf16 v[82:97], v[190:193], v[234:237], v[82:97]
	v_mfma_f32_32x32x16_bf16 v[18:33], v[190:193], v[238:241], v[18:33]
	ds_read_b128 v[190:193], v194 offset:8192
	v_lshl_add_u64 v[152:153], v[150:151], 0, s[48:49]
	s_mov_b32 m0, s9
	v_lshl_add_u64 v[150:151], v[150:151], 0, s[50:51]
	global_load_lds_dwordx4 v[152:153], off
	s_waitcnt lgkmcnt(5)
	v_mfma_f32_32x32x16_bf16 v[66:81], v[158:161], v[234:237], v[66:81]
	v_mfma_f32_32x32x16_bf16 v[2:17], v[158:161], v[238:241], v[2:17]
	ds_read_b128 v[158:161], v194 offset:12288
	v_add_u32_e32 v152, 0x6000, v154
	v_add_u32_e32 v155, 0x8000, v154
	v_readfirstlane_b32 s9, v152
	s_mov_b32 m0, s9
	v_readfirstlane_b32 s9, v155
	global_load_lds_dwordx4 v[150:151], off
	v_add_u32_e32 v189, v184, v140
	v_add_u32_e32 v194, v186, v140
	ds_read_b128 v[234:237], v189 offset:32768
	ds_read_b128 v[238:241], v189 offset:36864
	s_waitcnt lgkmcnt(5)
	v_mfma_f32_32x32x16_bf16 v[114:129], v[250:253], v[242:245], v[114:129]
	v_mfma_f32_32x32x16_bf16 v[50:65], v[250:253], v[246:249], v[50:65]
	ds_read_b128 v[250:253], v194
	v_lshl_add_u64 v[150:151], v[136:137], 0, s[34:35]
	v_add_u32_e32 v155, 0xa000, v154
	v_lshl_add_u64 v[152:153], v[150:151], 0, s[84:85]
	s_mov_b32 m0, s9
	v_readfirstlane_b32 s9, v155
	v_add_u32_e32 v155, 0xc000, v154
	global_load_lds_dwordx4 v[152:153], off
	s_waitcnt lgkmcnt(5)
	v_mfma_f32_32x32x16_bf16 v[98:113], v[180:183], v[242:245], v[98:113]
	v_mfma_f32_32x32x16_bf16 v[34:49], v[180:183], v[246:249], v[34:49]
	ds_read_b128 v[180:183], v194 offset:4096
	v_lshl_add_u64 v[152:153], v[150:151], 0, s[90:91]
	s_mov_b32 m0, s9
	v_readfirstlane_b32 s9, v155
	s_add_i32 s8, s5, 0xffff0000
	global_load_lds_dwordx4 v[152:153], off
	s_waitcnt lgkmcnt(5)
	v_mfma_f32_32x32x16_bf16 v[82:97], v[190:193], v[242:245], v[82:97]
	v_mfma_f32_32x32x16_bf16 v[18:33], v[190:193], v[246:249], v[18:33]
	ds_read_b128 v[190:193], v194 offset:8192
	v_lshl_add_u64 v[152:153], v[150:151], 0, s[48:49]
	s_mov_b32 m0, s9
	s_and_b32 s8, s8, 0x10000
	global_load_lds_dwordx4 v[152:153], off
	s_waitcnt lgkmcnt(5)
	v_mfma_f32_32x32x16_bf16 v[66:81], v[158:161], v[242:245], v[66:81]
	v_mfma_f32_32x32x16_bf16 v[2:17], v[158:161], v[246:249], v[2:17]
	ds_read_b128 v[158:161], v194 offset:12288
	v_add_u32_e32 v152, 0xe000, v154
	s_add_i32 s8, s8, 0
	v_readfirstlane_b32 s9, v152
	v_lshl_add_u64 v[150:151], v[150:151], 0, s[50:51]
	s_mov_b32 m0, s9
	v_add_u32_e32 v162, s8, v143
	v_add_u32_e32 v163, s8, v149
	global_load_lds_dwordx4 v[150:151], off
	v_add_u32_e32 v189, v184, v0
	v_add_u32_e32 v194, v186, v0
	ds_read_b128 v[242:245], v189 offset:32768
	ds_read_b128 v[246:249], v189 offset:36864
	s_waitcnt lgkmcnt(5)
	v_mfma_f32_32x32x16_bf16 v[114:129], v[250:253], v[234:237], v[114:129]
	v_mfma_f32_32x32x16_bf16 v[50:65], v[250:253], v[238:241], v[50:65]
	ds_read_b128 v[250:253], v194
	s_add_u32 s34, s34, 0x80
	s_addc_u32 s35, s35, 0
	s_add_i32 s5, s5, 0x10000
	s_cmpk_eq_i32 s34, 0x780
	s_waitcnt lgkmcnt(5)
	v_mfma_f32_32x32x16_bf16 v[98:113], v[180:183], v[234:237], v[98:113]
	v_mfma_f32_32x32x16_bf16 v[34:49], v[180:183], v[238:241], v[34:49]
	ds_read_b128 v[180:183], v194 offset:4096
	s_waitcnt lgkmcnt(5)
	v_mfma_f32_32x32x16_bf16 v[82:97], v[190:193], v[234:237], v[82:97]
	v_mfma_f32_32x32x16_bf16 v[18:33], v[190:193], v[238:241], v[18:33]
	ds_read_b128 v[190:193], v194 offset:8192
	s_waitcnt lgkmcnt(5)
	v_mfma_f32_32x32x16_bf16 v[66:81], v[158:161], v[234:237], v[66:81]
	v_mfma_f32_32x32x16_bf16 v[2:17], v[158:161], v[238:241], v[2:17]
	ds_read_b128 v[158:161], v194 offset:12288
	s_waitcnt lgkmcnt(3)
	v_mfma_f32_32x32x16_bf16 v[114:129], v[250:253], v[242:245], v[114:129]
	v_mfma_f32_32x32x16_bf16 v[50:65], v[250:253], v[246:249], v[50:65]
	s_waitcnt lgkmcnt(2)
	v_mfma_f32_32x32x16_bf16 v[98:113], v[180:183], v[242:245], v[98:113]
	v_mfma_f32_32x32x16_bf16 v[34:49], v[180:183], v[246:249], v[34:49]
	s_waitcnt lgkmcnt(1)
	v_mfma_f32_32x32x16_bf16 v[82:97], v[190:193], v[242:245], v[82:97]
	v_mfma_f32_32x32x16_bf16 v[18:33], v[190:193], v[246:249], v[18:33]
	s_waitcnt vmcnt(0) lgkmcnt(0)
	s_barrier
; DI f32x16 mfma(bf16x8 a, bf16x8 b, f32x16 c) { return __builtin_amdgcn_mfma_f32_32x32x16_bf16(a, b, c, 0, 0, 0); }
;     ...
;   for (int kt = 0; kt < nk; ++kt) {
;     const char* cur = lds + (kt & 1) * DBUF;
;     if (kt + 1 < nk) DMA_ISSUE((kt + 1) & 1, kt + 1)
; #pragma unroll(NTB == 1 ? 2 : 4)
;     for (int s = 0; s < 4; ++s) {
;       const int ro = ((2 * s + hh) ^ xr) * 16;
;       bf16x8 bfr[NTB];
; #pragma unroll
;       for (int tb = 0; tb < NTB; ++tb) bfr[tb] = *(const bf16x8*)(cur + bbase + tb * 32 * DROW + ro);
; #pragma unroll
;       for (int fb = 0; fb < NFB; ++fb) {
;         const bf16x8 afr = *(const bf16x8*)(cur + abase + fb * 32 * DROW + ro);
; #pragma unroll
;         for (int tb = 0; tb < NTB; ++tb) acc[tb * NFB + fb] = mfma(afr, bfr[tb], acc[tb * NFB + fb]);
;       }
;     }
;     asm volatile("s_waitcnt vmcnt(0) lgkmcnt(0)" ::: "memory");
;     __builtin_amdgcn_s_barrier();
;   }
	v_mfma_f32_32x32x16_bf16 v[66:81], v[158:161], v[242:245], v[66:81]
	v_mfma_f32_32x32x16_bf16 v[2:17], v[158:161], v[246:249], v[2:17]
	s_cbranch_scc0 .LBB0_174
	s_add_i32 s5, 0, 0x10000
	v_add_u32_e32 v158, s5, v143
	v_add_u32_e32 v159, s5, v149
	v_add_u32_e32 v142, v158, v148
	ds_read_b128 v[134:137], v142 offset:32768
	ds_read_b128 v[150:153], v142 offset:36864
	v_add_u32_e32 v142, v159, v148
	ds_read_b128 v[154:157], v142
	s_waitcnt lgkmcnt(0)
	v_mfma_f32_32x32x16_bf16 v[114:129], v[154:157], v[134:137], v[114:129]
	v_mfma_f32_32x32x16_bf16 v[50:65], v[154:157], v[150:153], v[50:65]
	ds_read_b128 v[154:157], v142 offset:4096
	s_waitcnt lgkmcnt(0)
	v_mfma_f32_32x32x16_bf16 v[98:113], v[154:157], v[134:137], v[98:113]
	v_mfma_f32_32x32x16_bf16 v[34:49], v[154:157], v[150:153], v[34:49]
	ds_read_b128 v[154:157], v142 offset:8192
	s_waitcnt lgkmcnt(0)
	v_mfma_f32_32x32x16_bf16 v[82:97], v[154:157], v[134:137], v[82:97]
	v_mfma_f32_32x32x16_bf16 v[18:33], v[154:157], v[150:153], v[18:33]
	ds_read_b128 v[154:157], v142 offset:12288
	v_add_u32_e32 v142, v158, v141
	v_add_u32_e32 v141, v159, v141
	s_waitcnt lgkmcnt(0)
	v_mfma_f32_32x32x16_bf16 v[66:81], v[154:157], v[134:137], v[66:81]
	v_mfma_f32_32x32x16_bf16 v[2:17], v[154:157], v[150:153], v[2:17]
	ds_read_b128 v[134:137], v142 offset:32768
	ds_read_b128 v[148:151], v142 offset:36864
	ds_read_b128 v[152:155], v141
	s_waitcnt lgkmcnt(0)
	v_mfma_f32_32x32x16_bf16 v[114:129], v[152:155], v[134:137], v[114:129]
	v_mfma_f32_32x32x16_bf16 v[50:65], v[152:155], v[148:151], v[50:65]
	ds_read_b128 v[152:155], v141 offset:4096
	s_waitcnt lgkmcnt(0)
	v_mfma_f32_32x32x16_bf16 v[98:113], v[152:155], v[134:137], v[98:113]
	v_mfma_f32_32x32x16_bf16 v[34:49], v[152:155], v[148:151], v[34:49]
	ds_read_b128 v[152:155], v141 offset:8192
	s_waitcnt lgkmcnt(0)
	v_mfma_f32_32x32x16_bf16 v[82:97], v[152:155], v[134:137], v[82:97]
	v_mfma_f32_32x32x16_bf16 v[18:33], v[152:155], v[148:151], v[18:33]
	ds_read_b128 v[152:155], v141 offset:12288
	v_add_u32_e32 v141, v158, v140
	s_waitcnt lgkmcnt(0)
	v_mfma_f32_32x32x16_bf16 v[66:81], v[152:155], v[134:137], v[66:81]
	v_mfma_f32_32x32x16_bf16 v[2:17], v[152:155], v[148:151], v[2:17]
	v_add_u32_e32 v152, v159, v140
	ds_read_b128 v[134:137], v141 offset:32768
	ds_read_b128 v[148:151], v141 offset:36864
	ds_read_b128 v[140:143], v152
	s_waitcnt lgkmcnt(0)
	v_mfma_f32_32x32x16_bf16 v[114:129], v[140:143], v[134:137], v[114:129]
	v_mfma_f32_32x32x16_bf16 v[50:65], v[140:143], v[148:151], v[50:65]
	ds_read_b128 v[140:143], v152 offset:4096
	s_waitcnt lgkmcnt(0)
	v_mfma_f32_32x32x16_bf16 v[98:113], v[140:143], v[134:137], v[98:113]
	v_mfma_f32_32x32x16_bf16 v[34:49], v[140:143], v[148:151], v[34:49]
	ds_read_b128 v[140:143], v152 offset:8192
	s_waitcnt lgkmcnt(0)
	v_mfma_f32_32x32x16_bf16 v[82:97], v[140:143], v[134:137], v[82:97]
	v_mfma_f32_32x32x16_bf16 v[18:33], v[140:143], v[148:151], v[18:33]
	ds_read_b128 v[140:143], v152 offset:12288
	s_waitcnt lgkmcnt(0)
	v_mfma_f32_32x32x16_bf16 v[66:81], v[140:143], v[134:137], v[66:81]
	v_mfma_f32_32x32x16_bf16 v[2:17], v[140:143], v[148:151], v[2:17]
	v_add_u32_e32 v140, v158, v0
	v_add_u32_e32 v0, v159, v0
	ds_read_b128 v[134:137], v140 offset:32768
	ds_read_b128 v[140:143], v140 offset:36864
	ds_read_b128 v[148:151], v0
	s_waitcnt lgkmcnt(0)
	v_mfma_f32_32x32x16_bf16 v[114:129], v[148:151], v[134:137], v[114:129]
	v_mfma_f32_32x32x16_bf16 v[50:65], v[148:151], v[140:143], v[50:65]
	ds_read_b128 v[148:151], v0 offset:4096
	s_waitcnt lgkmcnt(0)
	v_mfma_f32_32x32x16_bf16 v[98:113], v[148:151], v[134:137], v[98:113]
	v_mfma_f32_32x32x16_bf16 v[34:49], v[148:151], v[140:143], v[34:49]
	ds_read_b128 v[148:151], v0 offset:8192
	s_waitcnt lgkmcnt(0)
	v_mfma_f32_32x32x16_bf16 v[82:97], v[148:151], v[134:137], v[82:97]
	v_mfma_f32_32x32x16_bf16 v[18:33], v[148:151], v[140:143], v[18:33]
	ds_read_b128 v[148:151], v0 offset:12288
	s_waitcnt vmcnt(0) lgkmcnt(0)
	s_barrier
	s_waitcnt lgkmcnt(0)
	v_mfma_f32_32x32x16_bf16 v[66:81], v[148:151], v[134:137], v[66:81]
	v_mfma_f32_32x32x16_bf16 v[2:17], v[148:151], v[140:143], v[2:17]

; DI f32x16 mfma(bf16x8 a, bf16x8 b, f32x16 c) { return __builtin_amdgcn_mfma_f32_32x32x16_bf16(a, b, c, 0, 0, 0); }
;     ...
;   __syncthreads();
;   DMA_ISSUE(0, 0)
;   asm volatile("s_waitcnt vmcnt(0)" ::: "memory");
;   __builtin_amdgcn_s_barrier();
;   for (int kt = 0; kt < nk; ++kt) {
;     const char* cur = lds + (kt & 1) * DBUF;
;     if (kt + 1 < nk) DMA_ISSUE((kt + 1) & 1, kt + 1)
; #pragma unroll(NTB == 1 ? 2 : 4)
;     for (int s = 0; s < 4; ++s) {
;       const int ro = ((2 * s + hh) ^ xr) * 16;
;       bf16x8 bfr[NTB];
; #pragma unroll
;       for (int tb = 0; tb < NTB; ++tb) bfr[tb] = *(const bf16x8*)(cur + bbase + tb * 32 * DROW + ro);
; #pragma unroll
;       for (int fb = 0; fb < NFB; ++fb) {
;         const bf16x8 afr = *(const bf16x8*)(cur + abase + fb * 32 * DROW + ro);
; #pragma unroll
;         for (int tb = 0; tb < NTB; ++tb) acc[tb * NFB + fb] = mfma(afr, bfr[tb], acc[tb * NFB + fb]);
;       }
;     }
;     asm volatile("s_waitcnt vmcnt(0) lgkmcnt(0)" ::: "memory");
;     __builtin_amdgcn_s_barrier();
;   }
.LBB0_194:
	s_add_i32 s8, s1, 0xffff0000
	s_and_b32 s8, s8, 0x10000
	v_add_u32_e32 v184, s8, v137
	v_add_u32_e32 v186, s8, v139
	v_add_u32_e32 v189, v184, v138
	v_add_u32_e32 v194, v186, v138
	ds_read_b128 v[234:237], v189 offset:32768
	ds_read_b128 v[238:241], v189 offset:36864
	ds_read_b128 v[250:253], v194
	ds_read_b128 v[180:183], v194 offset:4096
	ds_read_b128 v[190:193], v194 offset:8192
	ds_read_b128 v[152:155], v194 offset:12288
	v_add_u32_e32 v189, v184, v135
	v_add_u32_e32 v194, v186, v135
	ds_read_b128 v[242:245], v189 offset:32768
	ds_read_b128 v[246:249], v189 offset:36864
	s_waitcnt lgkmcnt(5)
	v_mfma_f32_32x32x16_bf16 v[114:129], v[250:253], v[234:237], v[114:129]
	v_mfma_f32_32x32x16_bf16 v[50:65], v[250:253], v[238:241], v[50:65]
	ds_read_b128 v[250:253], v194
	s_and_b32 s9, s1, 0x10000
	v_add_u32_e32 v148, s9, v136
	v_lshl_add_u64 v[140:141], v[130:131], 0, s[4:5]
	s_mov_b64 s[10:11], 0xc90080
	v_readfirstlane_b32 s9, v148
	v_add_u32_e32 v149, 0x2000, v148
	v_lshl_add_u64 v[142:143], v[140:141], 0, s[10:11]
	s_mov_b32 m0, s9
	s_mov_b64 s[10:11], 0xcb0080
	v_readfirstlane_b32 s9, v149
	v_add_u32_e32 v149, 0x4000, v148
	global_load_lds_dwordx4 v[142:143], off
	s_waitcnt lgkmcnt(5)
	v_mfma_f32_32x32x16_bf16 v[98:113], v[180:183], v[234:237], v[98:113]
	v_mfma_f32_32x32x16_bf16 v[34:49], v[180:183], v[238:241], v[34:49]
	ds_read_b128 v[180:183], v194 offset:4096
	v_lshl_add_u64 v[142:143], v[140:141], 0, s[10:11]
	s_mov_b32 m0, s9
	s_mov_b64 s[10:11], 0xcd0080
	v_readfirstlane_b32 s9, v149
	global_load_lds_dwordx4 v[142:143], off
	s_waitcnt lgkmcnt(5)
	v_mfma_f32_32x32x16_bf16 v[82:97], v[190:193], v[234:237], v[82:97]
	v_mfma_f32_32x32x16_bf16 v[18:33], v[190:193], v[238:241], v[18:33]
	ds_read_b128 v[190:193], v194 offset:8192
	v_lshl_add_u64 v[142:143], v[140:141], 0, s[10:11]
	s_mov_b32 m0, s9
	s_mov_b64 s[10:11], 0xcf0080
	global_load_lds_dwordx4 v[142:143], off
	s_waitcnt lgkmcnt(5)
	v_mfma_f32_32x32x16_bf16 v[66:81], v[152:155], v[234:237], v[66:81]
	v_mfma_f32_32x32x16_bf16 v[2:17], v[152:155], v[238:241], v[2:17]
	ds_read_b128 v[152:155], v194 offset:12288
	v_add_u32_e32 v142, 0x6000, v148
	v_lshl_add_u64 v[140:141], v[140:141], 0, s[10:11]
	v_readfirstlane_b32 s9, v142
	s_mov_b32 m0, s9
	v_add_u32_e32 v149, 0x8000, v148
	global_load_lds_dwordx4 v[140:141], off
	v_add_u32_e32 v189, v184, v134
	v_add_u32_e32 v194, v186, v134
	ds_read_b128 v[234:237], v189 offset:32768
	ds_read_b128 v[238:241], v189 offset:36864
	s_waitcnt lgkmcnt(5)
	v_mfma_f32_32x32x16_bf16 v[114:129], v[250:253], v[242:245], v[114:129]
	v_mfma_f32_32x32x16_bf16 v[50:65], v[250:253], v[246:249], v[50:65]
	ds_read_b128 v[250:253], v194
	v_lshl_add_u64 v[140:141], v[132:133], 0, s[4:5]
	s_mov_b64 s[10:11], 0x6390080
	v_readfirstlane_b32 s9, v149
	v_add_u32_e32 v149, 0xa000, v148
	v_lshl_add_u64 v[142:143], v[140:141], 0, s[10:11]
	s_mov_b32 m0, s9
	s_mov_b64 s[10:11], 0x63b0080
	v_readfirstlane_b32 s9, v149
	v_add_u32_e32 v149, 0xc000, v148
	global_load_lds_dwordx4 v[142:143], off
	s_waitcnt lgkmcnt(5)
	v_mfma_f32_32x32x16_bf16 v[98:113], v[180:183], v[242:245], v[98:113]
	v_mfma_f32_32x32x16_bf16 v[34:49], v[180:183], v[246:249], v[34:49]
	ds_read_b128 v[180:183], v194 offset:4096
	v_lshl_add_u64 v[142:143], v[140:141], 0, s[10:11]
	s_mov_b32 m0, s9
	s_mov_b64 s[10:11], 0x63d0080
	v_readfirstlane_b32 s9, v149
	s_add_i32 s8, s1, 0xffff0000
	global_load_lds_dwordx4 v[142:143], off
	s_waitcnt lgkmcnt(5)
	v_mfma_f32_32x32x16_bf16 v[82:97], v[190:193], v[242:245], v[82:97]
	v_mfma_f32_32x32x16_bf16 v[18:33], v[190:193], v[246:249], v[18:33]
	ds_read_b128 v[190:193], v194 offset:8192
	v_lshl_add_u64 v[142:143], v[140:141], 0, s[10:11]
	s_mov_b32 m0, s9
	s_and_b32 s8, s8, 0x10000
	global_load_lds_dwordx4 v[142:143], off
	s_waitcnt lgkmcnt(5)
	v_mfma_f32_32x32x16_bf16 v[66:81], v[152:155], v[242:245], v[66:81]
	v_mfma_f32_32x32x16_bf16 v[2:17], v[152:155], v[246:249], v[2:17]
	ds_read_b128 v[152:155], v194 offset:12288
	v_add_u32_e32 v142, 0xe000, v148
	s_add_i32 s8, s8, 0
	s_mov_b64 s[10:11], 0x63f0080
	v_readfirstlane_b32 s9, v142
	v_lshl_add_u64 v[140:141], v[140:141], 0, s[10:11]
	s_mov_b32 m0, s9
	v_add_u32_e32 v156, s8, v137
	v_add_u32_e32 v157, s8, v139
	global_load_lds_dwordx4 v[140:141], off
	v_add_u32_e32 v189, v184, v0
	v_add_u32_e32 v194, v186, v0
	ds_read_b128 v[242:245], v189 offset:32768
	ds_read_b128 v[246:249], v189 offset:36864
	s_waitcnt lgkmcnt(5)
	v_mfma_f32_32x32x16_bf16 v[114:129], v[250:253], v[234:237], v[114:129]
	v_mfma_f32_32x32x16_bf16 v[50:65], v[250:253], v[238:241], v[50:65]
	ds_read_b128 v[250:253], v194
	s_add_u32 s4, s4, 0x80
	s_addc_u32 s5, s5, 0
	s_add_i32 s1, s1, 0x10000
	s_cmpk_eq_i32 s4, 0x780
	s_waitcnt lgkmcnt(5)
	v_mfma_f32_32x32x16_bf16 v[98:113], v[180:183], v[234:237], v[98:113]
	v_mfma_f32_32x32x16_bf16 v[34:49], v[180:183], v[238:241], v[34:49]
	ds_read_b128 v[180:183], v194 offset:4096
	s_waitcnt lgkmcnt(5)
	v_mfma_f32_32x32x16_bf16 v[82:97], v[190:193], v[234:237], v[82:97]
	v_mfma_f32_32x32x16_bf16 v[18:33], v[190:193], v[238:241], v[18:33]
	ds_read_b128 v[190:193], v194 offset:8192
	s_waitcnt lgkmcnt(5)
	v_mfma_f32_32x32x16_bf16 v[66:81], v[152:155], v[234:237], v[66:81]
	v_mfma_f32_32x32x16_bf16 v[2:17], v[152:155], v[238:241], v[2:17]
	ds_read_b128 v[152:155], v194 offset:12288
	s_waitcnt lgkmcnt(3)
	v_mfma_f32_32x32x16_bf16 v[114:129], v[250:253], v[242:245], v[114:129]
	v_mfma_f32_32x32x16_bf16 v[50:65], v[250:253], v[246:249], v[50:65]
	s_waitcnt lgkmcnt(2)
	v_mfma_f32_32x32x16_bf16 v[98:113], v[180:183], v[242:245], v[98:113]
	v_mfma_f32_32x32x16_bf16 v[34:49], v[180:183], v[246:249], v[34:49]
	s_waitcnt lgkmcnt(1)
	v_mfma_f32_32x32x16_bf16 v[82:97], v[190:193], v[242:245], v[82:97]
	v_mfma_f32_32x32x16_bf16 v[18:33], v[190:193], v[246:249], v[18:33]
	s_waitcnt vmcnt(0) lgkmcnt(0)
	s_barrier
; DI int get_tid() { int t = threadIdx.x; asm volatile("" : "+v"(t)); return t; }
; DI char* get_ws(const Params& p) { char* w = p.ws; asm volatile("" : "+s"(w)); return w; }
; DI float xsum32(float v) { const auto r = __builtin_amdgcn_permlane32_swap(__float_as_uint(v), __float_as_uint(v), false, false); return __uint_as_float(r[0]) + __uint_as_float(r[1]); }
; DI f32x16 mfma(bf16x8 a, bf16x8 b, f32x16 c) { return __builtin_amdgcn_mfma_f32_32x32x16_bf16(a, b, c, 0, 0, 0); }
; DI int perm16(int s) { return (s & ~12) | ((s & 4) << 1) | ((s & 8) >> 1); }
;     ...
;   for (int kt = 0; kt < nk; ++kt) {
;     const char* cur = lds + (kt & 1) * DBUF;
;     if (kt + 1 < nk) DMA_ISSUE((kt + 1) & 1, kt + 1)
; #pragma unroll(NTB == 1 ? 2 : 4)
;     for (int s = 0; s < 4; ++s) {
;       const int ro = ((2 * s + hh) ^ xr) * 16;
;       bf16x8 bfr[NTB];
; #pragma unroll
;       for (int tb = 0; tb < NTB; ++tb) bfr[tb] = *(const bf16x8*)(cur + bbase + tb * 32 * DROW + ro);
; #pragma unroll
;       for (int fb = 0; fb < NFB; ++fb) {
;         const bf16x8 afr = *(const bf16x8*)(cur + abase + fb * 32 * DROW + ro);
; #pragma unroll
;         for (int tb = 0; tb < NTB; ++tb) acc[tb * NFB + fb] = mfma(afr, bfr[tb], acc[tb * NFB + fb]);
;       }
;     }
;     asm volatile("s_waitcnt vmcnt(0) lgkmcnt(0)" ::: "memory");
;     __builtin_amdgcn_s_barrier();
;   }
; DI void memkv_epilogue(const Params& p, int l, int mt, int ft, f32x16* acc) {
;   char* ws = get_ws(p);
;   const int tid_ = get_tid(); const int lane = tid_ & 63, wave = tid_ >> 6, l32 = lane & 31, hh = lane >> 5;
;   const int b = mt >> 8, m = mt & 255;
;   if (ft < 4) {
;     const int head = ft;
;     float ss = sumsq16(acc[0]) + sumsq16(acc[1]) + sumsq16(acc[2]) + sumsq16(acc[3]);
;     ss = xsum32(ss);
;     const float rstd = rsqrtf(ss * (1.f / 128.f) + EPS);
;     const float* g = p.g_mem_k + l * 128;
;     u16* dst = (u16*)(ws + R_KM) + ((size_t)(b * 4 + head) * 256 + m) * 128;
; #pragma unroll
;     for (int fb = 0; fb < 4; ++fb) st_blk_scaled(dst + fb * 32, hh, acc[fb], rstd, g + fb * 32);
;   } else {
;     const int head = ft - 4;
;     u16* dst = (u16*)(ws + R_VM) + ((size_t)(b * 4 + head) * 128) * 256 + perm16(m);
	v_mfma_f32_32x32x16_bf16 v[66:81], v[152:155], v[242:245], v[66:81]
	v_mfma_f32_32x32x16_bf16 v[2:17], v[152:155], v[246:249], v[2:17]
	s_cbranch_scc0 .LBB0_194
	s_add_i32 s1, 0, 0x10000
	v_add_u32_e32 v148, s1, v137
	v_add_u32_e32 v149, s1, v139
	v_add_u32_e32 v136, v148, v138
	v_add_u32_e32 v150, v149, v138
	ds_read_b128 v[130:133], v136 offset:32768
	ds_read_b128 v[140:143], v136 offset:36864
	ds_read_b128 v[136:139], v150
	s_and_b32 s4, s6, -4
	s_waitcnt lgkmcnt(0)
	v_mfma_f32_32x32x16_bf16 v[114:129], v[136:139], v[130:133], v[114:129]
	v_mfma_f32_32x32x16_bf16 v[50:65], v[136:139], v[140:143], v[50:65]
	ds_read_b128 v[136:139], v150 offset:4096
	s_waitcnt lgkmcnt(0)
	v_mfma_f32_32x32x16_bf16 v[98:113], v[136:139], v[130:133], v[98:113]
	v_mfma_f32_32x32x16_bf16 v[34:49], v[136:139], v[140:143], v[34:49]
	ds_read_b128 v[136:139], v150 offset:8192
	s_waitcnt lgkmcnt(0)
	v_mfma_f32_32x32x16_bf16 v[82:97], v[136:139], v[130:133], v[82:97]
	v_mfma_f32_32x32x16_bf16 v[18:33], v[136:139], v[140:143], v[18:33]
	ds_read_b128 v[136:139], v150 offset:12288
	s_waitcnt lgkmcnt(0)
	v_mfma_f32_32x32x16_bf16 v[66:81], v[136:139], v[130:133], v[66:81]
	v_mfma_f32_32x32x16_bf16 v[2:17], v[136:139], v[140:143], v[2:17]
	v_add_u32_e32 v136, v148, v135
	v_add_u32_e32 v135, v149, v135
	ds_read_b128 v[130:133], v136 offset:32768
	ds_read_b128 v[136:139], v136 offset:36864
	ds_read_b128 v[140:143], v135
	s_waitcnt lgkmcnt(0)
	v_mfma_f32_32x32x16_bf16 v[114:129], v[140:143], v[130:133], v[114:129]
	v_mfma_f32_32x32x16_bf16 v[50:65], v[140:143], v[136:139], v[50:65]
	ds_read_b128 v[140:143], v135 offset:4096
	s_waitcnt lgkmcnt(0)
	v_mfma_f32_32x32x16_bf16 v[98:113], v[140:143], v[130:133], v[98:113]
	v_mfma_f32_32x32x16_bf16 v[34:49], v[140:143], v[136:139], v[34:49]
	ds_read_b128 v[140:143], v135 offset:8192
	s_waitcnt lgkmcnt(0)
	v_mfma_f32_32x32x16_bf16 v[82:97], v[140:143], v[130:133], v[82:97]
	v_mfma_f32_32x32x16_bf16 v[18:33], v[140:143], v[136:139], v[18:33]
	ds_read_b128 v[140:143], v135 offset:12288
	v_add_u32_e32 v135, v148, v134
	v_add_u32_e32 v134, v149, v134
	s_waitcnt lgkmcnt(0)
	v_mfma_f32_32x32x16_bf16 v[66:81], v[140:143], v[130:133], v[66:81]
	v_mfma_f32_32x32x16_bf16 v[2:17], v[140:143], v[136:139], v[2:17]
	ds_read_b128 v[130:133], v135 offset:32768
	ds_read_b128 v[136:139], v135 offset:36864
	ds_read_b128 v[140:143], v134
	s_waitcnt lgkmcnt(0)
	v_mfma_f32_32x32x16_bf16 v[114:129], v[140:143], v[130:133], v[114:129]
	v_mfma_f32_32x32x16_bf16 v[50:65], v[140:143], v[136:139], v[50:65]
	ds_read_b128 v[140:143], v134 offset:4096
	s_waitcnt lgkmcnt(0)
	v_mfma_f32_32x32x16_bf16 v[98:113], v[140:143], v[130:133], v[98:113]
	v_mfma_f32_32x32x16_bf16 v[34:49], v[140:143], v[136:139], v[34:49]
	ds_read_b128 v[140:143], v134 offset:8192
	s_waitcnt lgkmcnt(0)
	v_mfma_f32_32x32x16_bf16 v[82:97], v[140:143], v[130:133], v[82:97]
	v_mfma_f32_32x32x16_bf16 v[18:33], v[140:143], v[136:139], v[18:33]
	ds_read_b128 v[140:143], v134 offset:12288
	v_add_u32_e32 v134, v148, v0
	v_add_u32_e32 v0, v149, v0
	s_waitcnt lgkmcnt(0)
	v_mfma_f32_32x32x16_bf16 v[66:81], v[140:143], v[130:133], v[66:81]
	v_mfma_f32_32x32x16_bf16 v[2:17], v[140:143], v[136:139], v[2:17]
	ds_read_b128 v[130:133], v134 offset:32768
	ds_read_b128 v[134:137], v134 offset:36864
	ds_read_b128 v[138:141], v0
	s_waitcnt lgkmcnt(0)
	v_mfma_f32_32x32x16_bf16 v[114:129], v[138:141], v[130:133], v[114:129]
	v_mfma_f32_32x32x16_bf16 v[50:65], v[138:141], v[134:137], v[50:65]
	ds_read_b128 v[138:141], v0 offset:4096
	s_waitcnt lgkmcnt(0)
	v_mfma_f32_32x32x16_bf16 v[98:113], v[138:141], v[130:133], v[98:113]
	v_mfma_f32_32x32x16_bf16 v[34:49], v[138:141], v[134:137], v[34:49]
	ds_read_b128 v[138:141], v0 offset:8192
	s_waitcnt lgkmcnt(0)
	v_mfma_f32_32x32x16_bf16 v[82:97], v[138:141], v[130:133], v[82:97]
	v_mfma_f32_32x32x16_bf16 v[18:33], v[138:141], v[134:137], v[18:33]
	ds_read_b128 v[138:141], v0 offset:12288
	v_lshl_add_u32 v0, s7, 1, v146
	s_mov_b64 s[6:7], s[30:31]
	s_waitcnt vmcnt(0) lgkmcnt(0)
	s_barrier
	s_waitcnt lgkmcnt(0)
	v_mfma_f32_32x32x16_bf16 v[66:81], v[138:141], v[130:133], v[66:81]
	v_add_u32_e32 v130, s4, v0
	v_lshl_or_b32 v131, s0, 8, v231
	v_cmp_lt_i32_e64 s[0:1], 3, v0
	v_add_u32_e32 v0, -4, v130
	v_lshlrev_b64 v[132:133], 16, v[0:1]
	v_mov_b32_e32 v0, v145
	v_mfma_f32_32x32x16_bf16 v[2:17], v[138:141], v[134:137], v[2:17]
	v_bfe_u32 v136, v0, 5, 1
	v_lshlrev_b32_e32 v0, 1, v131
	v_or_b32_e32 v148, v131, v168
	v_and_b32_e32 v135, 8, v0
	s_and_saveexec_b64 s[4:5], s[0:1]
	s_xor_b64 s[4:5], exec, s[4:5]
	s_cbranch_execz .LBB0_197
; DI u16 tobf(float a) { return (u16)(pack2(a, 0.f) & 0xffffu); }
; DI int perm16(int s) { return (s & ~12) | ((s & 4) << 1) | ((s & 8) >> 1); }
; DI void memkv_epilogue(const Params& p, int l, int mt, int ft, f32x16* acc) {
;     ...
;   } else {
;     const int head = ft - 4;
;     u16* dst = (u16*)(ws + R_VM) + ((size_t)(b * 4 + head) * 128) * 256 + perm16(m);
; #pragma unroll
;     for (int fb = 0; fb < 4; ++fb)
; #pragma unroll
;       for (int i = 0; i < 16; ++i) {
;         const int d = fb * 32 + 8 * (i >> 2) + 4 * hh + (i & 3);
;         dst[(size_t)d * 256] = tobf(acc[fb][i]);
;       }
;   }
	v_and_b32_e32 v0, 0xd3, v148
	v_or3_b32 v0, v0, v135, v169
	v_lshl_add_u64 v[138:139], s[6:7], 0, v[132:133]
	v_lshlrev_b32_e32 v0, 1, v0
	v_lshl_add_u64 v[138:139], v[138:139], 0, v[0:1]
	v_lshlrev_b32_e32 v0, 11, v136
	v_lshl_add_u64 v[136:137], v[138:139], 0, v[0:1]
	s_mov_b64 s[2:3], 0x19bb1000
	v_lshl_add_u64 v[138:139], v[136:137], 0, s[2:3]
	v_add_co_u32_e32 v140, vcc, 0x19bb1000, v136
	v_cvt_pk_bf16_f32 v0, v115, s0
	v_cvt_pk_bf16_f32 v114, v114, s0
	v_addc_co_u32_e32 v141, vcc, 0, v137, vcc
	flat_store_short v[138:139], v0 offset:512
	v_cvt_pk_bf16_f32 v0, v116, s0
	s_mov_b32 s2, 0x19bb2000
	flat_store_short v[140:141], v114
	flat_store_short v[138:139], v0 offset:1024
	v_cvt_pk_bf16_f32 v0, v117, s0
	v_add_co_u32_e32 v114, vcc, s2, v136
	flat_store_short v[138:139], v0 offset:1536
	v_cvt_pk_bf16_f32 v0, v118, s0
	v_addc_co_u32_e32 v115, vcc, 0, v137, vcc
	flat_store_short v[114:115], v0
	v_cvt_pk_bf16_f32 v0, v119, s0
	flat_store_short v[114:115], v0 offset:512
	v_cvt_pk_bf16_f32 v0, v120, s0
	flat_store_short v[114:115], v0 offset:1024
	v_cvt_pk_bf16_f32 v0, v121, s0
	s_mov_b32 s2, 0x19bb3000
	flat_store_short v[114:115], v0 offset:1536
	v_add_co_u32_e32 v114, vcc, s2, v136
	v_cvt_pk_bf16_f32 v0, v122, s0
	s_nop 0
	v_addc_co_u32_e32 v115, vcc, 0, v137, vcc
	flat_store_short v[114:115], v0
	v_cvt_pk_bf16_f32 v0, v123, s0
	flat_store_short v[114:115], v0 offset:512
	v_cvt_pk_bf16_f32 v0, v124, s0
	flat_store_short v[114:115], v0 offset:1024
	v_cvt_pk_bf16_f32 v0, v125, s0
	s_mov_b32 s2, 0x19bb4000
	flat_store_short v[114:115], v0 offset:1536
	v_add_co_u32_e32 v114, vcc, s2, v136
	v_cvt_pk_bf16_f32 v0, v126, s0
	s_nop 0
	v_addc_co_u32_e32 v115, vcc, 0, v137, vcc
	flat_store_short v[114:115], v0
	v_cvt_pk_bf16_f32 v0, v127, s0
	flat_store_short v[114:115], v0 offset:512
	v_cvt_pk_bf16_f32 v0, v128, s0
	flat_store_short v[114:115], v0 offset:1024
	v_cvt_pk_bf16_f32 v0, v129, s0
	s_mov_b32 s2, 0x19bb5000
	flat_store_short v[114:115], v0 offset:1536
	v_add_co_u32_e32 v114, vcc, s2, v136
	v_cvt_pk_bf16_f32 v0, v98, s0
	s_nop 0
	v_addc_co_u32_e32 v115, vcc, 0, v137, vcc
	flat_store_short v[114:115], v0
	v_cvt_pk_bf16_f32 v0, v99, s0
	flat_store_short v[114:115], v0 offset:512
	v_cvt_pk_bf16_f32 v0, v100, s0
	s_mov_b32 s2, 0x19bb6000
	flat_store_short v[114:115], v0 offset:1024
	v_cvt_pk_bf16_f32 v0, v101, s0
	v_add_co_u32_e32 v98, vcc, s2, v136
	flat_store_short v[114:115], v0 offset:1536
	v_cvt_pk_bf16_f32 v0, v102, s0
	v_addc_co_u32_e32 v99, vcc, 0, v137, vcc
	flat_store_short v[98:99], v0
	v_cvt_pk_bf16_f32 v0, v103, s0
	flat_store_short v[98:99], v0 offset:512
	v_cvt_pk_bf16_f32 v0, v104, s0
	flat_store_short v[98:99], v0 offset:1024
	v_cvt_pk_bf16_f32 v0, v105, s0
	s_mov_b32 s2, 0x19bb7000
	flat_store_short v[98:99], v0 offset:1536
	v_add_co_u32_e32 v98, vcc, s2, v136
	v_cvt_pk_bf16_f32 v0, v106, s0
	s_nop 0
	v_addc_co_u32_e32 v99, vcc, 0, v137, vcc
	flat_store_short v[98:99], v0
	v_cvt_pk_bf16_f32 v0, v107, s0
	flat_store_short v[98:99], v0 offset:512
	v_cvt_pk_bf16_f32 v0, v108, s0
	flat_store_short v[98:99], v0 offset:1024
	v_cvt_pk_bf16_f32 v0, v109, s0
	s_mov_b32 s2, 0x19bb8000
	flat_store_short v[98:99], v0 offset:1536
	v_add_co_u32_e32 v98, vcc, s2, v136
	v_cvt_pk_bf16_f32 v0, v110, s0
	s_nop 0
	v_addc_co_u32_e32 v99, vcc, 0, v137, vcc
	flat_store_short v[98:99], v0
	v_cvt_pk_bf16_f32 v0, v111, s0
	flat_store_short v[98:99], v0 offset:512
	v_cvt_pk_bf16_f32 v0, v112, s0
	flat_store_short v[98:99], v0 offset:1024
	v_cvt_pk_bf16_f32 v0, v113, s0
	s_mov_b32 s8, 0x19bb9000
	flat_store_short v[98:99], v0 offset:1536
	v_add_co_u32_e32 v98, vcc, s8, v136
	v_cvt_pk_bf16_f32 v0, v82, s0
	s_nop 0
	v_addc_co_u32_e32 v99, vcc, 0, v137, vcc
	flat_store_short v[98:99], v0
	v_cvt_pk_bf16_f32 v0, v83, s0
	flat_store_short v[98:99], v0 offset:512
	v_cvt_pk_bf16_f32 v0, v84, s0
	s_mov_b32 s2, 0x19bba000
	flat_store_short v[98:99], v0 offset:1024
	v_cvt_pk_bf16_f32 v0, v85, s0
	v_add_co_u32_e32 v82, vcc, s2, v136
	flat_store_short v[98:99], v0 offset:1536
	v_cvt_pk_bf16_f32 v0, v86, s0
	v_addc_co_u32_e32 v83, vcc, 0, v137, vcc
	flat_store_short v[82:83], v0
	v_cvt_pk_bf16_f32 v0, v87, s0
	flat_store_short v[82:83], v0 offset:512
	v_cvt_pk_bf16_f32 v0, v88, s0
	flat_store_short v[82:83], v0 offset:1024
	v_cvt_pk_bf16_f32 v0, v89, s0
	s_mov_b32 s2, 0x19bbb000
	flat_store_short v[82:83], v0 offset:1536
	v_add_co_u32_e32 v82, vcc, s2, v136
	v_cvt_pk_bf16_f32 v0, v90, s0
	s_nop 0
	v_addc_co_u32_e32 v83, vcc, 0, v137, vcc
	flat_store_short v[82:83], v0
	v_cvt_pk_bf16_f32 v0, v91, s0
	flat_store_short v[82:83], v0 offset:512
	v_cvt_pk_bf16_f32 v0, v92, s0
	flat_store_short v[82:83], v0 offset:1024
	v_cvt_pk_bf16_f32 v0, v93, s0
	s_mov_b32 s2, 0x19bbc000
	flat_store_short v[82:83], v0 offset:1536
	v_add_co_u32_e32 v82, vcc, s2, v136
	v_cvt_pk_bf16_f32 v0, v94, s0
	s_nop 0
	v_addc_co_u32_e32 v83, vcc, 0, v137, vcc
	flat_store_short v[82:83], v0
	v_cvt_pk_bf16_f32 v0, v95, s0
	flat_store_short v[82:83], v0 offset:512
	v_cvt_pk_bf16_f32 v0, v96, s0
	flat_store_short v[82:83], v0 offset:1024
	v_cvt_pk_bf16_f32 v0, v97, s0
	s_mov_b32 s2, 0x19bbd000
	flat_store_short v[82:83], v0 offset:1536
	v_add_co_u32_e32 v82, vcc, s2, v136
	v_cvt_pk_bf16_f32 v0, v66, s0
	s_nop 0
	v_addc_co_u32_e32 v83, vcc, 0, v137, vcc
	flat_store_short v[82:83], v0
	v_cvt_pk_bf16_f32 v0, v67, s0
	flat_store_short v[82:83], v0 offset:512
	v_cvt_pk_bf16_f32 v0, v68, s0
	s_mov_b32 s2, 0x19bbe000
	flat_store_short v[82:83], v0 offset:1024
	v_cvt_pk_bf16_f32 v0, v69, s0
	v_add_co_u32_e32 v66, vcc, s2, v136
	flat_store_short v[82:83], v0 offset:1536
	v_cvt_pk_bf16_f32 v0, v70, s0
	v_addc_co_u32_e32 v67, vcc, 0, v137, vcc
	flat_store_short v[66:67], v0
	v_cvt_pk_bf16_f32 v0, v71, s0
	flat_store_short v[66:67], v0 offset:512
	v_cvt_pk_bf16_f32 v0, v72, s0
	flat_store_short v[66:67], v0 offset:1024
	v_cvt_pk_bf16_f32 v0, v73, s0
	s_mov_b32 s2, 0x19bbf000
	flat_store_short v[66:67], v0 offset:1536
	v_add_co_u32_e32 v66, vcc, s2, v136
	v_cvt_pk_bf16_f32 v0, v74, s0
	s_nop 0
	v_addc_co_u32_e32 v67, vcc, 0, v137, vcc
	flat_store_short v[66:67], v0
	v_cvt_pk_bf16_f32 v0, v75, s0
	flat_store_short v[66:67], v0 offset:512
	v_cvt_pk_bf16_f32 v0, v76, s0
	flat_store_short v[66:67], v0 offset:1024
	v_cvt_pk_bf16_f32 v0, v77, s0
	flat_store_short v[66:67], v0 offset:1536
	v_add_co_u32_e32 v66, vcc, 0x19bc0000, v136
	v_cvt_pk_bf16_f32 v0, v78, s0
	s_nop 0
	v_addc_co_u32_e32 v67, vcc, 0, v137, vcc
	flat_store_short v[66:67], v0
	v_cvt_pk_bf16_f32 v0, v79, s0
	flat_store_short v[66:67], v0 offset:512
	v_cvt_pk_bf16_f32 v0, v80, s0
	flat_store_short v[66:67], v0 offset:1024
	v_cvt_pk_bf16_f32 v0, v81, s0
	flat_store_short v[66:67], v0 offset:1536

; DI f32x16 mfma(bf16x8 a, bf16x8 b, f32x16 c) { return __builtin_amdgcn_mfma_f32_32x32x16_bf16(a, b, c, 0, 0, 0); }
;     ...
;   __syncthreads();
;   DMA_ISSUE(0, 0)
;   asm volatile("s_waitcnt vmcnt(0)" ::: "memory");
;   __builtin_amdgcn_s_barrier();
;   for (int kt = 0; kt < nk; ++kt) {
;     const char* cur = lds + (kt & 1) * DBUF;
;     if (kt + 1 < nk) DMA_ISSUE((kt + 1) & 1, kt + 1)
; #pragma unroll(NTB == 1 ? 2 : 4)
;     for (int s = 0; s < 4; ++s) {
;       const int ro = ((2 * s + hh) ^ xr) * 16;
;       bf16x8 bfr[NTB];
; #pragma unroll
;       for (int tb = 0; tb < NTB; ++tb) bfr[tb] = *(const bf16x8*)(cur + bbase + tb * 32 * DROW + ro);
; #pragma unroll
;       for (int fb = 0; fb < NFB; ++fb) {
;         const bf16x8 afr = *(const bf16x8*)(cur + abase + fb * 32 * DROW + ro);
; #pragma unroll
;         for (int tb = 0; tb < NTB; ++tb) acc[tb * NFB + fb] = mfma(afr, bfr[tb], acc[tb * NFB + fb]);
;       }
;     }
;     asm volatile("s_waitcnt vmcnt(0) lgkmcnt(0)" ::: "memory");
;     __builtin_amdgcn_s_barrier();
;   }
.LBB0_206:
	s_add_i32 s5, s1, 0xffff0000
	s_and_b32 s5, s5, 0x10000
	v_add_u32_e32 v184, s5, v137
	v_add_u32_e32 v186, s5, v139
	v_add_u32_e32 v189, v184, v138
	v_add_u32_e32 v194, v186, v138
	ds_read_b128 v[234:237], v189 offset:32768
	ds_read_b128 v[238:241], v189 offset:36864
	ds_read_b128 v[250:253], v194
	ds_read_b128 v[180:183], v194 offset:4096
	ds_read_b128 v[190:193], v194 offset:8192
	ds_read_b128 v[152:155], v194 offset:12288
	v_add_u32_e32 v189, v184, v136
	v_add_u32_e32 v194, v186, v136
	ds_read_b128 v[242:245], v189 offset:32768
	ds_read_b128 v[246:249], v189 offset:36864
	s_waitcnt lgkmcnt(5)
	v_mfma_f32_32x32x16_bf16 v[114:129], v[250:253], v[234:237], v[114:129]
	v_mfma_f32_32x32x16_bf16 v[50:65], v[250:253], v[238:241], v[50:65]
	ds_read_b128 v[250:253], v194
	s_and_b32 s9, s1, 0x10000
	v_add_u32_e32 v148, s9, v135
	v_lshl_add_u64 v[140:141], v[130:131], 0, s[6:7]
	v_readfirstlane_b32 s9, v148
	v_add_u32_e32 v149, 0x2000, v148
	v_lshl_add_u64 v[142:143], v[140:141], 0, s[84:85]
	s_mov_b32 m0, s9
	v_readfirstlane_b32 s9, v149
	v_add_u32_e32 v149, 0x4000, v148
	global_load_lds_dwordx4 v[142:143], off
	s_waitcnt lgkmcnt(5)
	v_mfma_f32_32x32x16_bf16 v[98:113], v[180:183], v[234:237], v[98:113]
	v_mfma_f32_32x32x16_bf16 v[34:49], v[180:183], v[238:241], v[34:49]
	ds_read_b128 v[180:183], v194 offset:4096
	v_lshl_add_u64 v[142:143], v[140:141], 0, s[90:91]
	s_mov_b32 m0, s9
	v_readfirstlane_b32 s9, v149
	global_load_lds_dwordx4 v[142:143], off
	s_waitcnt lgkmcnt(5)
	v_mfma_f32_32x32x16_bf16 v[82:97], v[190:193], v[234:237], v[82:97]
	v_mfma_f32_32x32x16_bf16 v[18:33], v[190:193], v[238:241], v[18:33]
	ds_read_b128 v[190:193], v194 offset:8192
	v_lshl_add_u64 v[142:143], v[140:141], 0, s[48:49]
	s_mov_b32 m0, s9
	v_lshl_add_u64 v[140:141], v[140:141], 0, s[50:51]
	global_load_lds_dwordx4 v[142:143], off
	s_waitcnt lgkmcnt(5)
	v_mfma_f32_32x32x16_bf16 v[66:81], v[152:155], v[234:237], v[66:81]
	v_mfma_f32_32x32x16_bf16 v[2:17], v[152:155], v[238:241], v[2:17]
	ds_read_b128 v[152:155], v194 offset:12288
	v_add_u32_e32 v142, 0x6000, v148
	v_add_u32_e32 v149, 0x8000, v148
	v_readfirstlane_b32 s9, v142
	s_mov_b32 m0, s9
	v_readfirstlane_b32 s9, v149
	global_load_lds_dwordx4 v[140:141], off
	v_add_u32_e32 v189, v184, v134
	v_add_u32_e32 v194, v186, v134
	ds_read_b128 v[234:237], v189 offset:32768
	ds_read_b128 v[238:241], v189 offset:36864
	s_waitcnt lgkmcnt(5)
	v_mfma_f32_32x32x16_bf16 v[114:129], v[250:253], v[242:245], v[114:129]
	v_mfma_f32_32x32x16_bf16 v[50:65], v[250:253], v[246:249], v[50:65]
	ds_read_b128 v[250:253], v194
	v_lshl_add_u64 v[140:141], v[132:133], 0, s[6:7]
	v_add_u32_e32 v149, 0xa000, v148
	v_lshl_add_u64 v[142:143], v[140:141], 0, s[10:11]
	s_mov_b32 m0, s9
	v_readfirstlane_b32 s9, v149
	v_add_u32_e32 v149, 0xc000, v148
	global_load_lds_dwordx4 v[142:143], off
	s_waitcnt lgkmcnt(5)
	v_mfma_f32_32x32x16_bf16 v[98:113], v[180:183], v[242:245], v[98:113]
	v_mfma_f32_32x32x16_bf16 v[34:49], v[180:183], v[246:249], v[34:49]
	ds_read_b128 v[180:183], v194 offset:4096
	v_lshl_add_u64 v[142:143], v[140:141], 0, s[12:13]
	s_mov_b32 m0, s9
	v_readfirstlane_b32 s9, v149
	s_add_i32 s5, s1, 0xffff0000
	global_load_lds_dwordx4 v[142:143], off
	s_waitcnt lgkmcnt(5)
	v_mfma_f32_32x32x16_bf16 v[82:97], v[190:193], v[242:245], v[82:97]
	v_mfma_f32_32x32x16_bf16 v[18:33], v[190:193], v[246:249], v[18:33]
	ds_read_b128 v[190:193], v194 offset:8192
	v_lshl_add_u64 v[142:143], v[140:141], 0, s[14:15]
	s_mov_b32 m0, s9
	s_and_b32 s5, s5, 0x10000
	global_load_lds_dwordx4 v[142:143], off
	s_waitcnt lgkmcnt(5)
	v_mfma_f32_32x32x16_bf16 v[66:81], v[152:155], v[242:245], v[66:81]
	v_mfma_f32_32x32x16_bf16 v[2:17], v[152:155], v[246:249], v[2:17]
	ds_read_b128 v[152:155], v194 offset:12288
	v_add_u32_e32 v142, 0xe000, v148
	s_add_i32 s5, s5, 0
	v_readfirstlane_b32 s9, v142
	v_lshl_add_u64 v[140:141], v[140:141], 0, s[40:41]
	s_mov_b32 m0, s9
	v_add_u32_e32 v156, s5, v137
	v_add_u32_e32 v157, s5, v139
	global_load_lds_dwordx4 v[140:141], off
	v_add_u32_e32 v189, v184, v0
	v_add_u32_e32 v194, v186, v0
	ds_read_b128 v[242:245], v189 offset:32768
	ds_read_b128 v[246:249], v189 offset:36864
	s_waitcnt lgkmcnt(5)
	v_mfma_f32_32x32x16_bf16 v[114:129], v[250:253], v[234:237], v[114:129]
	v_mfma_f32_32x32x16_bf16 v[50:65], v[250:253], v[238:241], v[50:65]
	ds_read_b128 v[250:253], v194
	s_add_u32 s6, s6, 0x80
	s_addc_u32 s7, s7, 0
	s_add_i32 s1, s1, 0x10000
	s_cmpk_eq_i32 s6, 0x780
	s_waitcnt lgkmcnt(5)
	v_mfma_f32_32x32x16_bf16 v[98:113], v[180:183], v[234:237], v[98:113]
	v_mfma_f32_32x32x16_bf16 v[34:49], v[180:183], v[238:241], v[34:49]
	ds_read_b128 v[180:183], v194 offset:4096
	s_waitcnt lgkmcnt(5)
	v_mfma_f32_32x32x16_bf16 v[82:97], v[190:193], v[234:237], v[82:97]
	v_mfma_f32_32x32x16_bf16 v[18:33], v[190:193], v[238:241], v[18:33]
	ds_read_b128 v[190:193], v194 offset:8192
	s_waitcnt lgkmcnt(5)
	v_mfma_f32_32x32x16_bf16 v[66:81], v[152:155], v[234:237], v[66:81]
	v_mfma_f32_32x32x16_bf16 v[2:17], v[152:155], v[238:241], v[2:17]
	ds_read_b128 v[152:155], v194 offset:12288
	s_waitcnt lgkmcnt(3)
	v_mfma_f32_32x32x16_bf16 v[114:129], v[250:253], v[242:245], v[114:129]
	v_mfma_f32_32x32x16_bf16 v[50:65], v[250:253], v[246:249], v[50:65]
	s_waitcnt lgkmcnt(2)
	v_mfma_f32_32x32x16_bf16 v[98:113], v[180:183], v[242:245], v[98:113]
	v_mfma_f32_32x32x16_bf16 v[34:49], v[180:183], v[246:249], v[34:49]
	s_waitcnt lgkmcnt(1)
	v_mfma_f32_32x32x16_bf16 v[82:97], v[190:193], v[242:245], v[82:97]
	v_mfma_f32_32x32x16_bf16 v[18:33], v[190:193], v[246:249], v[18:33]
	s_waitcnt vmcnt(0) lgkmcnt(0)
	s_barrier
; DI f32x16 mfma(bf16x8 a, bf16x8 b, f32x16 c) { return __builtin_amdgcn_mfma_f32_32x32x16_bf16(a, b, c, 0, 0, 0); }
;     ...
;   for (int kt = 0; kt < nk; ++kt) {
;     const char* cur = lds + (kt & 1) * DBUF;
;     if (kt + 1 < nk) DMA_ISSUE((kt + 1) & 1, kt + 1)
; #pragma unroll(NTB == 1 ? 2 : 4)
;     for (int s = 0; s < 4; ++s) {
;       const int ro = ((2 * s + hh) ^ xr) * 16;
;       bf16x8 bfr[NTB];
; #pragma unroll
;       for (int tb = 0; tb < NTB; ++tb) bfr[tb] = *(const bf16x8*)(cur + bbase + tb * 32 * DROW + ro);
; #pragma unroll
;       for (int fb = 0; fb < NFB; ++fb) {
;         const bf16x8 afr = *(const bf16x8*)(cur + abase + fb * 32 * DROW + ro);
; #pragma unroll
;         for (int tb = 0; tb < NTB; ++tb) acc[tb * NFB + fb] = mfma(afr, bfr[tb], acc[tb * NFB + fb]);
;       }
;     }
;     asm volatile("s_waitcnt vmcnt(0) lgkmcnt(0)" ::: "memory");
;     __builtin_amdgcn_s_barrier();
;   }
; __global__ void __launch_bounds__(512) mega(Params p) {
;     ...
;           for (int tb = 0; tb < 2; ++tb) {
;             const int t = tt * 256 + wt * 64 + tb * 32 + l32;
;             const float r1 = rstd4((const float*)(ws + OFF_SSX1) + (size_t)(l & 1) * 4 * T_TOK, t);
	v_mfma_f32_32x32x16_bf16 v[66:81], v[152:155], v[242:245], v[66:81]
	v_mfma_f32_32x32x16_bf16 v[2:17], v[152:155], v[246:249], v[2:17]
	s_cbranch_scc0 .LBB0_206
	s_add_i32 s1, 0, 0x10000
	v_add_u32_e32 v160, s1, v139
	v_add_u32_e32 v135, v160, v138
	ds_read_b128 v[130:133], v135
	v_add_u32_e32 v161, s1, v137
	v_add_u32_e32 v137, v161, v138
	ds_read_b128 v[138:141], v137 offset:32768
	ds_read_b128 v[148:151], v137 offset:36864
	ds_read_b128 v[152:155], v135 offset:4096
	s_mov_b32 s1, 0x20000
	s_waitcnt lgkmcnt(0)
	v_mfma_f32_32x32x16_bf16 v[98:113], v[152:155], v[138:141], v[98:113]
	s_mov_b64 s[64:65], s[30:31]
	v_mfma_f32_32x32x16_bf16 v[114:129], v[130:133], v[138:141], v[114:129]
	v_mfma_f32_32x32x16_bf16 v[50:65], v[130:133], v[148:151], v[50:65]
	v_mfma_f32_32x32x16_bf16 v[34:49], v[152:155], v[148:151], v[34:49]
	ds_read_b128 v[130:133], v135 offset:8192
	ds_read_b128 v[152:155], v135 offset:12288
	v_add_u32_e32 v135, v160, v136
	s_waitcnt lgkmcnt(0)
	v_mfma_f32_32x32x16_bf16 v[82:97], v[130:133], v[138:141], v[82:97]
	v_mfma_f32_32x32x16_bf16 v[18:33], v[130:133], v[148:151], v[18:33]
	ds_read_b128 v[130:133], v135
	v_mfma_f32_32x32x16_bf16 v[66:81], v[152:155], v[138:141], v[66:81]
	v_add_u32_e32 v140, v161, v136
	v_mfma_f32_32x32x16_bf16 v[2:17], v[152:155], v[148:151], v[2:17]
	ds_read_b128 v[136:139], v140 offset:32768
	ds_read_b128 v[140:143], v140 offset:36864
	ds_read_b128 v[148:151], v135 offset:4096
	s_waitcnt lgkmcnt(0)
	v_mfma_f32_32x32x16_bf16 v[114:129], v[130:133], v[136:139], v[114:129]
	v_mfma_f32_32x32x16_bf16 v[50:65], v[130:133], v[140:143], v[50:65]
	v_mfma_f32_32x32x16_bf16 v[98:113], v[148:151], v[136:139], v[98:113]
	v_mfma_f32_32x32x16_bf16 v[34:49], v[148:151], v[140:143], v[34:49]
	ds_read_b128 v[130:133], v135 offset:8192
	ds_read_b128 v[148:151], v135 offset:12288
	s_waitcnt lgkmcnt(0)
	v_mfma_f32_32x32x16_bf16 v[82:97], v[130:133], v[136:139], v[82:97]
	v_mfma_f32_32x32x16_bf16 v[66:81], v[148:151], v[136:139], v[66:81]
	v_add_u32_e32 v138, v160, v134
	v_add_u32_e32 v139, v161, v134
	v_mfma_f32_32x32x16_bf16 v[18:33], v[130:133], v[140:143], v[18:33]
	ds_read_b128 v[130:133], v138
	ds_read_b128 v[134:137], v139 offset:32768
	ds_read_b128 v[152:155], v139 offset:36864
	ds_read_b128 v[156:159], v138 offset:4096
	ds_read_b128 v[162:165], v138 offset:8192
	ds_read_b128 v[172:175], v138 offset:12288
	v_add_u32_e32 v138, v161, v0
	v_add_u32_e32 v0, v160, v0
	v_mfma_f32_32x32x16_bf16 v[2:17], v[148:151], v[140:143], v[2:17]
	v_lshl_or_b32 v148, s4, 8, v170
	v_ashrrev_i32_e32 v149, 31, v148
	v_lshl_add_u64 v[160:161], v[148:149], 2, s[24:25]
	ds_read_b128 v[176:179], v138 offset:32768
	ds_read_b128 v[138:141], v138 offset:36864
	ds_read_b128 v[180:183], v0
	ds_read_b128 v[232:235], v0 offset:4096
	ds_read_b128 v[236:239], v0 offset:8192
	ds_read_b128 v[240:243], v0 offset:12288
	s_waitcnt vmcnt(0) lgkmcnt(0)
	s_waitcnt lgkmcnt(0)
	v_mfma_f32_32x32x16_bf16 v[114:129], v[130:133], v[134:137], v[114:129]
	s_barrier
; DI void g1_epilogue(const Params& p, int l, int t, int ft, f32x16* acc, bool do_atomic) {
;   char* ws = get_ws(p);
;   const int tid_ = get_tid(); const int lane = tid_ & 63, wave = tid_ >> 6, l32 = lane & 31, hh = lane >> 5;
;   const int b = t >> 12, s = t & 4095;
;   if (ft < 5) {
;     u16* dst; float* ssp;
;     if (ft < 3) { dst = (u16*)(ws + R_CQ) + (size_t)t * 384 + ft * 128; ssp = (float*)(ws + OFF_SSQ) + (size_t)ft * T_TOK + t; }
;     else { dst = (u16*)(ws + R_CKV) + (size_t)t * 256 + (ft - 3) * 128; ssp = (float*)(ws + OFF_SSKV) + (size_t)(ft - 3) * T_TOK + t; }
;     float ss = 0.f;
; #pragma unroll
;     for (int fb = 0; fb < 4; ++fb) {
;       ss += sumsq16(acc[fb]);
;       st_blk_plain(dst + fb * 32, hh, acc[fb]);
;     }
;     ss = xsum32(ss);
;     if (hh == 0) *ssp = ss;
;   } else if (ft < 13) {
;     const bool isq = ft < 9; const int head = isq ? ft - 5 : ft - 9;
;     const float* g = (isq ? p.g_diff_q : p.g_diff_k) + l * 64;
;     u16* base = (u16*)(ws + (isq ? R_DQ : R_DK));
;     const float mul = isq ? 0.125f * LOG2E : 1.f;
; #pragma unroll
;     for (int c = 0; c < 2; ++c) {
;       float ss = sumsq16(acc[2 * c]) + sumsq16(acc[2 * c + 1]);
;       ss = xsum32(ss);
;       const float rstd = rsqrtf(ss * (1.f / 64.f) + EPS) * mul;
;       u16* dst = base + (((size_t)(b * 4 + head) * 2 + c) * 4096 + s) * 64;
; #pragma unroll
;       for (int fbb = 0; fbb < 2; ++fbb) st_blk_scaled(dst + fbb * 32, hh, acc[2 * c + fbb], rstd, g + fbb * 32);
;     }
;   } else if (ft < 17) {
;     const int head = ft - 13;
;     u16* dst = (u16*)(ws + R_DV) + ((size_t)(b * 4 + head) * 128) * 4096 + perm16(s);
; #pragma unroll
;     for (int fb = 0; fb < 4; ++fb)
; #pragma unroll
;       for (int i = 0; i < 16; ++i) {
;         const int d = fb * 32 + 8 * (i >> 2) + 4 * hh + (i & 3);
;         dst[(size_t)d * 4096] = tobf(acc[fb][i]);
;       }
; __global__ void __launch_bounds__(512) mega(Params p) {
;     ...
;           for (int tb = 0; tb < 2; ++tb) {
;             const int t = tt * 256 + wt * 64 + tb * 32 + l32;
;             const float r1 = rstd4((const float*)(ws + OFF_SSX1) + (size_t)(l & 1) * 4 * T_TOK, t);
; #pragma unroll
;             for (int fb = 0; fb < 4; ++fb)
; #pragma unroll
;               for (int i = 0; i < 16; ++i) acc[tb * 4 + fb][i] *= r1;
;             g1_epilogue(p, l, t, ft * 2 + wf, acc + tb * 4, (p.flags & 1) == 0);
	v_mfma_f32_32x32x16_bf16 v[50:65], v[130:133], v[152:155], v[50:65]
	v_add_co_u32_e32 v130, vcc, s1, v160
	s_mov_b32 s1, 0x40000
	s_nop 0
	v_addc_co_u32_e32 v131, vcc, 0, v161, vcc
	v_add_co_u32_e32 v132, vcc, s1, v160
	s_mov_b32 s1, 0x60000
	s_nop 0
	v_addc_co_u32_e32 v133, vcc, 0, v161, vcc
	v_add_co_u32_e32 v142, vcc, s1, v160
	v_mfma_f32_32x32x16_bf16 v[98:113], v[156:159], v[134:137], v[98:113]
	s_nop 0
	v_addc_co_u32_e32 v143, vcc, 0, v161, vcc
	v_mfma_f32_32x32x16_bf16 v[34:49], v[156:159], v[152:155], v[34:49]
	flat_load_dword v0, v[160:161]
	flat_load_dword v157, v[130:131]
	s_nop 0
	flat_load_dword v132, v[132:133]
	s_nop 0
	flat_load_dword v133, v[142:143]
	v_lshl_add_u32 v156, s0, 1, v146
	s_ashr_i32 s0, s8, 2
	v_subrev_co_u32_e32 v130, vcc, 17, v156
	s_and_b32 s0, s0, -4
	v_add_u32_e32 v130, s0, v130
	v_mfma_f32_32x32x16_bf16 v[82:97], v[162:165], v[134:137], v[82:97]
	s_xor_b64 s[42:43], vcc, -1
	v_subrev_co_u32_e32 v150, vcc, 13, v156
	v_ashrrev_i32_e32 v131, 31, v130
	v_lshlrev_b64 v[142:143], 20, v[130:131]
	v_add_u32_e32 v130, s0, v150
	v_ashrrev_i32_e32 v131, 31, v130
	v_mfma_f32_32x32x16_bf16 v[66:81], v[172:175], v[134:137], v[66:81]
	s_xor_b64 s[52:53], vcc, -1
	v_lshlrev_b64 v[150:151], 20, v[130:131]
	v_cmp_gt_u32_e32 vcc, 9, v156
	v_mov_b32_e32 v130, 0x3e38aa3b
	v_readlane_b32 s8, v255, 14
	v_cndmask_b32_e32 v171, 1.0, v130, vcc
	v_mov_b32_e32 v130, 0xb9b1000
	v_mfma_f32_32x32x16_bf16 v[18:33], v[162:165], v[152:155], v[18:33]
	v_mov_b32_e32 v131, 0x99b1000
	v_readlane_b32 s19, v255, 25
	v_readlane_b32 s21, v255, 27
	v_cndmask_b32_e32 v158, v130, v131, vcc
	v_readlane_b32 s18, v255, 24
	v_readlane_b32 s20, v255, 26
	v_mov_b32_e32 v130, s21
	v_mfma_f32_32x32x16_bf16 v[2:17], v[172:175], v[152:155], v[2:17]
	v_mov_b32_e32 v131, s19
	v_cndmask_b32_e32 v131, v130, v131, vcc
	v_mov_b32_e32 v130, s20
	v_mov_b32_e32 v135, s18
	v_cndmask_b32_e32 v130, v130, v135, vcc
	v_cndmask_b32_e64 v134, -9, -5, vcc
	v_lshl_add_u64 v[154:155], s[74:75], 2, v[130:131]
	v_mfma_f32_32x32x16_bf16 v[114:129], v[180:183], v[176:179], v[114:129]
	v_add3_u32 v130, v156, s0, v134
	v_cmp_lt_i32_e64 s[6:7], 4, v156
	v_cmp_lt_u32_e64 s[4:5], 20, v156
	v_mov_b32_e32 v159, v1
	v_cmp_lt_i32_e64 s[0:1], 2, v156
	v_readlane_b32 s9, v255, 15
	v_mfma_f32_32x32x16_bf16 v[98:113], v[232:235], v[176:179], v[98:113]
	v_readlane_b32 s10, v255, 16
	v_readlane_b32 s11, v255, 17
	v_readlane_b32 s12, v255, 18
	v_readlane_b32 s13, v255, 19
	v_readlane_b32 s14, v255, 20
	v_readlane_b32 s15, v255, 21
	v_readlane_b32 s16, v255, 22
	v_mfma_f32_32x32x16_bf16 v[82:97], v[236:239], v[176:179], v[82:97]
	v_readlane_b32 s17, v255, 23
	v_readlane_b32 s22, v255, 28
	v_readlane_b32 s23, v255, 29
	s_waitcnt vmcnt(0) lgkmcnt(0)
	v_add_f32_e32 v0, v0, v157
	v_add_f32_e32 v0, v0, v132
	v_add_f32_e32 v0, v0, v133
	v_fmamk_f32 v0, v0, 0x3a800000, v144
	v_mul_f32_e32 v131, 0x4b800000, v0
	v_cmp_gt_f32_e32 vcc, s47, v0
	v_mfma_f32_32x32x16_bf16 v[66:81], v[240:243], v[176:179], v[66:81]
	s_nop 0
	v_cndmask_b32_e32 v0, v0, v131, vcc
	v_rsq_f32_e32 v0, v0
	v_ashrrev_i32_e32 v131, 31, v130
	v_lshlrev_b64 v[152:153], 20, v[130:131]
	v_mul_f32_e32 v130, 0x45800000, v0
	v_mfma_f32_32x32x16_bf16 v[50:65], v[180:183], v[138:141], v[50:65]
	v_cndmask_b32_e32 v0, v0, v130, vcc
	v_mul_f32_e64 v134, v0, v114
	v_mul_f32_e64 v135, v0, v115
	v_mul_f32_e64 v136, v0, v116
	v_mul_f32_e64 v137, v0, v117
	v_pk_mul_f32 v[130:131], v[0:1], v[118:119] op_sel_hi:[0,1]
	v_pk_mul_f32 v[132:133], v[0:1], v[120:121] op_sel_hi:[0,1]
	v_pk_mul_f32 v[118:119], v[0:1], v[122:123] op_sel_hi:[0,1]
	v_pk_mul_f32 v[120:121], v[0:1], v[124:125] op_sel_hi:[0,1]
	v_mfma_f32_32x32x16_bf16 v[34:49], v[232:235], v[138:141], v[34:49]
	v_mul_f32_e64 v114, v0, v126
	v_mul_f32_e64 v115, v0, v127
	v_mul_f32_e64 v116, v0, v128
	v_mul_f32_e64 v117, v0, v129
	v_mul_f32_e64 v166, v0, v98
	v_mul_f32_e64 v167, v0, v99
	v_pk_mul_f32 v[164:165], v[0:1], v[100:101] op_sel_hi:[0,1]
	v_pk_mul_f32 v[162:163], v[0:1], v[102:103] op_sel_hi:[0,1]
	v_pk_mul_f32 v[128:129], v[0:1], v[104:105] op_sel_hi:[0,1]
	v_pk_mul_f32 v[126:127], v[0:1], v[106:107] op_sel_hi:[0,1]
	v_mfma_f32_32x32x16_bf16 v[18:33], v[236:239], v[138:141], v[18:33]
	v_mul_f32_e64 v124, v0, v108
	v_mul_f32_e64 v125, v0, v109
	v_mul_f32_e64 v122, v0, v110
	v_mul_f32_e64 v123, v0, v111
	v_mul_f32_e64 v110, v0, v112
	v_mul_f32_e64 v111, v0, v113
	v_pk_mul_f32 v[108:109], v[0:1], v[82:83] op_sel_hi:[0,1]
	v_pk_mul_f32 v[106:107], v[0:1], v[84:85] op_sel_hi:[0,1]
	v_pk_mul_f32 v[104:105], v[0:1], v[86:87] op_sel_hi:[0,1]
	v_pk_mul_f32 v[102:103], v[0:1], v[88:89] op_sel_hi:[0,1]
	v_mfma_f32_32x32x16_bf16 v[2:17], v[240:243], v[138:141], v[2:17]
	v_mul_f32_e64 v100, v0, v90
	v_mul_f32_e64 v101, v0, v91
	v_mul_f32_e64 v98, v0, v92
	v_mul_f32_e64 v99, v0, v93
	v_mul_f32_e64 v94, v0, v94
	v_mul_f32_e64 v95, v0, v95
	v_pk_mul_f32 v[92:93], v[0:1], v[96:97] op_sel_hi:[0,1]
	v_pk_mul_f32 v[90:91], v[0:1], v[66:67] op_sel_hi:[0,1]
	v_pk_mul_f32 v[88:89], v[0:1], v[68:69] op_sel_hi:[0,1]
	v_pk_mul_f32 v[86:87], v[0:1], v[70:71] op_sel_hi:[0,1]
	v_pk_mul_f32 v[84:85], v[0:1], v[72:73] op_sel_hi:[0,1]
	v_pk_mul_f32 v[82:83], v[0:1], v[74:75] op_sel_hi:[0,1]
	v_pk_mul_f32 v[74:75], v[0:1], v[76:77] op_sel_hi:[0,1]
	v_pk_mul_f32 v[72:73], v[0:1], v[78:79] op_sel_hi:[0,1]
	v_pk_mul_f32 v[70:71], v[0:1], v[80:81] op_sel_hi:[0,1]
	v_mov_b32_e32 v0, v145
	s_nop 0
	v_bfe_u32 v78, v0, 5, 1
	s_and_saveexec_b64 s[8:9], s[6:7]
	s_xor_b64 s[66:67], exec, s[8:9]
	s_cbranch_execz .LBB0_221
	v_and_b32_e32 v68, 0xfdf, v148
	s_and_saveexec_b64 s[8:9], s[52:53]
	s_xor_b64 s[10:11], exec, s[8:9]
	s_cbranch_execz .LBB0_218
	s_and_saveexec_b64 s[8:9], s[42:43]
	s_xor_b64 s[34:35], exec, s[8:9]
	s_cbranch_execz .LBB0_215
	s_and_saveexec_b64 s[8:9], s[4:5]
	s_xor_b64 s[8:9], exec, s[8:9]
	s_cbranch_execz .LBB0_212
	v_lshlrev_b64 v[66:67], 7, v[148:149]
	v_lshl_add_u64 v[66:67], s[64:65], 0, v[66:67]
	v_lshlrev_b32_e32 v0, 4, v78
	v_lshl_add_u64 v[66:67], v[66:67], 0, v[0:1]
	s_mov_b64 s[68:69], 0x95b1000
	v_lshl_add_u64 v[68:69], v[66:67], 0, s[68:69]
	v_add_co_u32_e32 v66, vcc, 0x95b1000, v66
	s_nop 1
	v_addc_co_u32_e32 v67, vcc, 0, v67, vcc
	flat_store_dwordx4 v[66:67], v[134:137]
	flat_store_dwordx4 v[68:69], v[130:133] offset:32
	flat_store_dwordx4 v[68:69], v[118:121] offset:64
	flat_store_dwordx4 v[68:69], v[114:117] offset:96
